# counted vmcnt waits: staged row groups written to LDS as they land; second X2 pair does not wait for the first pair's stores
# speedup vs baseline: 1.0041x; 1.0009x over previous
; #define MFMA16(a, b, c) __builtin_amdgcn_mfma_f32_16x16x32_bf16((a), (b), (c), 0, 0, 0)
; __device__ __forceinline__ void sample_out_block(LAS unsigned char* lds, const bf16_t* A, const bf16_t* Bt, int K, bf16_t* xb, float* sspart, int blk, int tid) {
;     ...
;     {
;         const bf16_t* ap = A + (size_t)(r0 + l15) * K + wave * kq + 8 * g;
;         const bf16_t* bp = Bt + (size_t)(64 * cg + l15) * K + wave * kq + 8 * g;
;         bf16x8 af[2][2], bf[2][4], afn[2][2], bfn[2][4];
; #pragma unroll
;         for (int s = 0; s < 2; ++s) {
; #pragma unroll
;             for (int ra = 0; ra < 2; ++ra) af[s][ra] = *(const bf16x8*)(ap + (size_t)(16 * ra) * K + 32 * s);
; #pragma unroll
;             for (int nt = 0; nt < 4; ++nt) bf[s][nt] = *(const bf16x8*)(bp + (size_t)(16 * nt) * K + 32 * s);
;         }
;         for (int k0 = 0; k0 < kq; k0 += 64) {
;             const int k1 = (k0 + 64 < kq) ? k0 + 64 : k0;
; #pragma unroll
;             for (int s = 0; s < 2; ++s) {
; #pragma unroll
;                 for (int ra = 0; ra < 2; ++ra) afn[s][ra] = *(const bf16x8*)(ap + (size_t)(16 * ra) * K + k1 + 32 * s);
; #pragma unroll
;                 for (int nt = 0; nt < 4; ++nt) bfn[s][nt] = *(const bf16x8*)(bp + (size_t)(16 * nt) * K + k1 + 32 * s);
;             }
; #pragma unroll
;             for (int s = 0; s < 2; ++s)
; #pragma unroll
;                 for (int ra = 0; ra < 2; ++ra)
; #pragma unroll
;                     for (int nt = 0; nt < 4; ++nt) acc[ra][nt] = MFMA16(af[s][ra], bf[s][nt], acc[ra][nt]);
.LBB0_542:
	s_and_b32 s27, s34, 0xffffffe0
	s_addk_i32 s27, 0x2000
	s_and_b32 s26, s34, 31
	v_or_b32_e32 v8, s27, v30
	v_ashrrev_i32_e32 v9, 31, v8
	s_lshl_b32 s35, s26, 6
	v_lshlrev_b64 v[8:9], 13, v[8:9]
	v_or_b32_e32 v0, s35, v30
	v_lshl_add_u64 v[10:11], v[2:3], 0, v[8:9]
	v_lshlrev_b32_e32 v0, 13, v0
	v_lshl_add_u64 v[16:17], v[4:5], 0, v[0:1]
	v_add_co_u32_e32 v8, vcc, 0x20000, v10
	s_mov_b64 s[10:11], vcc
	v_add_co_u32_e32 v12, vcc, 0x20000, v16
	v_readfirstlane_b32 s36, v139
	s_lshr_b32 s36, s36, 6
	s_and_b32 s37, s34, 0xffffffe0
	s_addk_i32 s37, 0x2000
	s_and_b32 s38, s34, 31
	s_lshl_b32 s38, s38, 6
	s_lshl_b32 s39, s37, 13
	s_mul_i32 s40, s36, 0x400
	s_add_u32 s42, s24, s39
	s_addc_u32 s43, s25, 0
	s_add_u32 s42, s42, s40
	s_addc_u32 s43, s43, 0
	s_lshl_b32 s41, s30, 1
	s_lshl_b32 s39, s38, 13
	s_add_u32 s44, s28, s41
	s_addc_u32 s45, s29, 0
	s_add_u32 s44, s44, s39
	s_addc_u32 s45, s45, 0
	s_add_u32 s44, s44, s40
	s_addc_u32 s45, s45, 0
	v_lshrrev_b32_e32 v227, 3, v215
	v_and_b32_e32 v228, 7, v215
	v_lshlrev_b32_e32 v198, 13, v227
	v_lshl_add_u32 v198, v228, 4, v198
	v_add_u32_e32 v199, 0x10000, v198
	v_add_u32_e32 v200, 0x20000, v198
	v_add_u32_e32 v201, 0x30000, v198
	v_add_u32_e32 v202, 0x40000, v198
	v_add_u32_e32 v203, 0x50000, v198
	v_add_u32_e32 v204, 0x60000, v198
	v_add_u32_e32 v205, 0x70000, v198
	s_lshl_b32 s46, s36, 13
	s_mul_i32 s47, s36, 0x1800
	s_add_i32 s47, s47, 0x10000
	v_mul_u32_u24_e32 v206, 0x90, v227
	v_lshl_add_u32 v206, v228, 4, v206
	v_add_u32_e32 v207, s47, v206
	v_add_u32_e32 v206, s46, v206
	v_and_b32_e32 v227, 15, v215
	v_lshrrev_b32_e32 v228, 4, v215
	v_mul_u32_u24_e32 v208, 0x90, v227
	v_lshl_add_u32 v208, v228, 4, v208
	v_add_u32_e32 v209, s47, v208
	v_add_u32_e32 v208, s46, v208
	v_add_u32_e32 v226, 0x1b00, v208
	v_subrev_u32_e32 v228, 0x480, v209
	v_cmp_gt_u32_e32 vcc, 8, v227
	v_cndmask_b32_e32 v226, v228, v226, vcc
	global_load_dwordx4 v[34:37], v198, s[42:43]
	global_load_dwordx4 v[38:41], v199, s[42:43]
	global_load_dwordx4 v[42:45], v200, s[42:43]
	global_load_dwordx4 v[46:49], v201, s[42:43]
	global_load_dwordx4 v[50:53], v198, s[44:45]
	global_load_dwordx4 v[54:57], v199, s[44:45]
	global_load_dwordx4 v[58:61], v200, s[44:45]
	global_load_dwordx4 v[62:65], v201, s[44:45]
	global_load_dwordx4 v[66:69], v202, s[44:45]
	global_load_dwordx4 v[70:73], v203, s[44:45]
	global_load_dwordx4 v[74:77], v204, s[44:45]
	global_load_dwordx4 v[78:81], v205, s[44:45]
	global_load_dwordx4 v[82:85], v198, s[42:43] offset:128
	global_load_dwordx4 v[86:89], v199, s[42:43] offset:128
	global_load_dwordx4 v[90:93], v200, s[42:43] offset:128
	global_load_dwordx4 v[94:97], v201, s[42:43] offset:128
	global_load_dwordx4 v[98:101], v198, s[44:45] offset:128
	global_load_dwordx4 v[102:105], v199, s[44:45] offset:128
	global_load_dwordx4 v[106:109], v200, s[44:45] offset:128
	global_load_dwordx4 v[110:113], v201, s[44:45] offset:128
	global_load_dwordx4 v[114:117], v202, s[44:45] offset:128
	global_load_dwordx4 v[118:121], v203, s[44:45] offset:128
	global_load_dwordx4 v[122:125], v204, s[44:45] offset:128
	global_load_dwordx4 v[126:129], v205, s[44:45] offset:128
	s_waitcnt vmcnt(23)
	ds_write_b128 v206, v[34:37]
	s_waitcnt vmcnt(22)
	ds_write_b128 v206, v[38:41] offset:1152
	s_waitcnt vmcnt(21)
	ds_write_b128 v206, v[42:45] offset:2304
	s_waitcnt vmcnt(20)
	ds_write_b128 v206, v[46:49] offset:3456
	s_waitcnt vmcnt(19)
	ds_write_b128 v206, v[50:53] offset:4608
	s_waitcnt vmcnt(18)
	ds_write_b128 v206, v[54:57] offset:5760
	s_waitcnt vmcnt(17)
	ds_write_b128 v206, v[58:61] offset:6912
	s_waitcnt vmcnt(16)
	ds_write_b128 v207, v[62:65]
	s_waitcnt vmcnt(15)
	ds_write_b128 v207, v[66:69] offset:1152
	s_waitcnt vmcnt(14)
	ds_write_b128 v207, v[70:73] offset:2304
	s_waitcnt vmcnt(13)
	ds_write_b128 v207, v[74:77] offset:3456
	s_waitcnt vmcnt(12)
	ds_write_b128 v207, v[78:81] offset:4608
	global_load_dwordx4 v[34:37], v198, s[42:43] offset:256
	global_load_dwordx4 v[38:41], v199, s[42:43] offset:256
	global_load_dwordx4 v[42:45], v200, s[42:43] offset:256
	global_load_dwordx4 v[46:49], v201, s[42:43] offset:256
	global_load_dwordx4 v[50:53], v198, s[44:45] offset:256
	global_load_dwordx4 v[54:57], v199, s[44:45] offset:256
	global_load_dwordx4 v[58:61], v200, s[44:45] offset:256
	global_load_dwordx4 v[62:65], v201, s[44:45] offset:256
	global_load_dwordx4 v[66:69], v202, s[44:45] offset:256
	global_load_dwordx4 v[70:73], v203, s[44:45] offset:256
	global_load_dwordx4 v[74:77], v204, s[44:45] offset:256
	global_load_dwordx4 v[78:81], v205, s[44:45] offset:256
	ds_read_b128 v[146:149], v208 offset:0
	ds_read_b128 v[150:153], v208 offset:2304
	ds_read_b128 v[154:157], v208 offset:4608
	ds_read_b128 v[158:161], v226
	ds_read_b128 v[162:165], v209 offset:1152
	ds_read_b128 v[166:169], v209 offset:3456
	ds_read_b128 v[170:173], v208 offset:64
	ds_read_b128 v[174:177], v208 offset:2368
	ds_read_b128 v[178:181], v208 offset:4672
	ds_read_b128 v[182:185], v226 offset:64
	ds_read_b128 v[186:189], v209 offset:1216
	ds_read_b128 v[190:193], v209 offset:3520
	s_waitcnt lgkmcnt(6)
	v_mfma_f32_16x16x32_bf16 v[8:11], v[146:149], v[154:157], 0
	v_mfma_f32_16x16x32_bf16 v[12:15], v[146:149], v[158:161], 0
	v_mfma_f32_16x16x32_bf16 v[16:19], v[146:149], v[162:165], 0
	v_mfma_f32_16x16x32_bf16 v[20:23], v[146:149], v[166:169], 0
	v_mfma_f32_16x16x32_bf16 v[24:27], v[150:153], v[154:157], 0
	v_mfma_f32_16x16x32_bf16 v[130:133], v[150:153], v[158:161], 0
	v_mfma_f32_16x16x32_bf16 v[134:137], v[150:153], v[162:165], 0
	v_mfma_f32_16x16x32_bf16 v[194:197], v[150:153], v[166:169], 0
	s_waitcnt lgkmcnt(0)
; #define MFMA16(a, b, c) __builtin_amdgcn_mfma_f32_16x16x32_bf16((a), (b), (c), 0, 0, 0)
; __device__ __forceinline__ void sample_out_block(LAS unsigned char* lds, const bf16_t* A, const bf16_t* Bt, int K, bf16_t* xb, float* sspart, int blk, int tid) {
;     ...
;         for (int k0 = 0; k0 < kq; k0 += 64) {
;             const int k1 = (k0 + 64 < kq) ? k0 + 64 : k0;
; #pragma unroll
;             for (int s = 0; s < 2; ++s) {
; #pragma unroll
;                 for (int ra = 0; ra < 2; ++ra) afn[s][ra] = *(const bf16x8*)(ap + (size_t)(16 * ra) * K + k1 + 32 * s);
; #pragma unroll
;                 for (int nt = 0; nt < 4; ++nt) bfn[s][nt] = *(const bf16x8*)(bp + (size_t)(16 * nt) * K + k1 + 32 * s);
;             }
; #pragma unroll
;             for (int s = 0; s < 2; ++s)
; #pragma unroll
;                 for (int ra = 0; ra < 2; ++ra)
; #pragma unroll
;                     for (int nt = 0; nt < 4; ++nt) acc[ra][nt] = MFMA16(af[s][ra], bf[s][nt], acc[ra][nt]);
	v_mfma_f32_16x16x32_bf16 v[8:11], v[170:173], v[178:181], v[8:11]
	v_mfma_f32_16x16x32_bf16 v[12:15], v[170:173], v[182:185], v[12:15]
	v_mfma_f32_16x16x32_bf16 v[16:19], v[170:173], v[186:189], v[16:19]
	v_mfma_f32_16x16x32_bf16 v[20:23], v[170:173], v[190:193], v[20:23]
	v_mfma_f32_16x16x32_bf16 v[24:27], v[174:177], v[178:181], v[24:27]
	v_mfma_f32_16x16x32_bf16 v[130:133], v[174:177], v[182:185], v[130:133]
	v_mfma_f32_16x16x32_bf16 v[134:137], v[174:177], v[186:189], v[134:137]
	v_mfma_f32_16x16x32_bf16 v[194:197], v[174:177], v[190:193], v[194:197]
	s_waitcnt vmcnt(23)
	ds_write_b128 v206, v[82:85]
	s_waitcnt vmcnt(22)
	ds_write_b128 v206, v[86:89] offset:1152
	s_waitcnt vmcnt(21)
	ds_write_b128 v206, v[90:93] offset:2304
	s_waitcnt vmcnt(20)
	ds_write_b128 v206, v[94:97] offset:3456
	s_waitcnt vmcnt(19)
	ds_write_b128 v206, v[98:101] offset:4608
	s_waitcnt vmcnt(18)
	ds_write_b128 v206, v[102:105] offset:5760
	s_waitcnt vmcnt(17)
	ds_write_b128 v206, v[106:109] offset:6912
	s_waitcnt vmcnt(16)
	ds_write_b128 v207, v[110:113]
	s_waitcnt vmcnt(15)
	ds_write_b128 v207, v[114:117] offset:1152
	s_waitcnt vmcnt(14)
	ds_write_b128 v207, v[118:121] offset:2304
	s_waitcnt vmcnt(13)
	ds_write_b128 v207, v[122:125] offset:3456
	s_waitcnt vmcnt(12)
	ds_write_b128 v207, v[126:129] offset:4608
	global_load_dwordx4 v[82:85], v198, s[42:43] offset:384
	global_load_dwordx4 v[86:89], v199, s[42:43] offset:384
	global_load_dwordx4 v[90:93], v200, s[42:43] offset:384
	global_load_dwordx4 v[94:97], v201, s[42:43] offset:384
	global_load_dwordx4 v[98:101], v198, s[44:45] offset:384
	global_load_dwordx4 v[102:105], v199, s[44:45] offset:384
	global_load_dwordx4 v[106:109], v200, s[44:45] offset:384
	global_load_dwordx4 v[110:113], v201, s[44:45] offset:384
	global_load_dwordx4 v[114:117], v202, s[44:45] offset:384
	global_load_dwordx4 v[118:121], v203, s[44:45] offset:384
	global_load_dwordx4 v[122:125], v204, s[44:45] offset:384
	global_load_dwordx4 v[126:129], v205, s[44:45] offset:384
	ds_read_b128 v[146:149], v208 offset:0
	ds_read_b128 v[150:153], v208 offset:2304
	ds_read_b128 v[154:157], v208 offset:4608
	ds_read_b128 v[158:161], v226
	ds_read_b128 v[162:165], v209 offset:1152
	ds_read_b128 v[166:169], v209 offset:3456
	ds_read_b128 v[170:173], v208 offset:64
	ds_read_b128 v[174:177], v208 offset:2368
	ds_read_b128 v[178:181], v208 offset:4672
	ds_read_b128 v[182:185], v226 offset:64
	ds_read_b128 v[186:189], v209 offset:1216
	ds_read_b128 v[190:193], v209 offset:3520
	s_waitcnt lgkmcnt(6)
	v_mfma_f32_16x16x32_bf16 v[8:11], v[146:149], v[154:157], v[8:11]
	v_mfma_f32_16x16x32_bf16 v[12:15], v[146:149], v[158:161], v[12:15]
	v_mfma_f32_16x16x32_bf16 v[16:19], v[146:149], v[162:165], v[16:19]
	v_mfma_f32_16x16x32_bf16 v[20:23], v[146:149], v[166:169], v[20:23]
	v_mfma_f32_16x16x32_bf16 v[24:27], v[150:153], v[154:157], v[24:27]
	v_mfma_f32_16x16x32_bf16 v[130:133], v[150:153], v[158:161], v[130:133]
	v_mfma_f32_16x16x32_bf16 v[134:137], v[150:153], v[162:165], v[134:137]
	v_mfma_f32_16x16x32_bf16 v[194:197], v[150:153], v[166:169], v[194:197]
	s_waitcnt lgkmcnt(0)
	v_mfma_f32_16x16x32_bf16 v[8:11], v[170:173], v[178:181], v[8:11]
	v_mfma_f32_16x16x32_bf16 v[12:15], v[170:173], v[182:185], v[12:15]
	v_mfma_f32_16x16x32_bf16 v[16:19], v[170:173], v[186:189], v[16:19]
	v_mfma_f32_16x16x32_bf16 v[20:23], v[170:173], v[190:193], v[20:23]
	v_mfma_f32_16x16x32_bf16 v[24:27], v[174:177], v[178:181], v[24:27]
	v_mfma_f32_16x16x32_bf16 v[130:133], v[174:177], v[182:185], v[130:133]
	v_mfma_f32_16x16x32_bf16 v[134:137], v[174:177], v[186:189], v[134:137]
	v_mfma_f32_16x16x32_bf16 v[194:197], v[174:177], v[190:193], v[194:197]
	s_waitcnt vmcnt(23)
	ds_write_b128 v206, v[34:37]
	s_waitcnt vmcnt(22)
	ds_write_b128 v206, v[38:41] offset:1152
	s_waitcnt vmcnt(21)
	ds_write_b128 v206, v[42:45] offset:2304
	s_waitcnt vmcnt(20)
	ds_write_b128 v206, v[46:49] offset:3456
	s_waitcnt vmcnt(19)
	ds_write_b128 v206, v[50:53] offset:4608
	s_waitcnt vmcnt(18)
	ds_write_b128 v206, v[54:57] offset:5760
	s_waitcnt vmcnt(17)
	ds_write_b128 v206, v[58:61] offset:6912
	s_waitcnt vmcnt(16)
	ds_write_b128 v207, v[62:65]
	s_waitcnt vmcnt(15)
	ds_write_b128 v207, v[66:69] offset:1152
	s_waitcnt vmcnt(14)
	ds_write_b128 v207, v[70:73] offset:2304
	s_waitcnt vmcnt(13)
	ds_write_b128 v207, v[74:77] offset:3456
	s_waitcnt vmcnt(12)
	ds_write_b128 v207, v[78:81] offset:4608
	global_load_dwordx4 v[34:37], v198, s[42:43] offset:512
	global_load_dwordx4 v[38:41], v199, s[42:43] offset:512
	global_load_dwordx4 v[42:45], v200, s[42:43] offset:512
	global_load_dwordx4 v[46:49], v201, s[42:43] offset:512
	global_load_dwordx4 v[50:53], v198, s[44:45] offset:512
	global_load_dwordx4 v[54:57], v199, s[44:45] offset:512
	global_load_dwordx4 v[58:61], v200, s[44:45] offset:512
	global_load_dwordx4 v[62:65], v201, s[44:45] offset:512
	global_load_dwordx4 v[66:69], v202, s[44:45] offset:512
	global_load_dwordx4 v[70:73], v203, s[44:45] offset:512
	global_load_dwordx4 v[74:77], v204, s[44:45] offset:512
	global_load_dwordx4 v[78:81], v205, s[44:45] offset:512
	ds_read_b128 v[146:149], v208 offset:0
	ds_read_b128 v[150:153], v208 offset:2304
	ds_read_b128 v[154:157], v208 offset:4608
	ds_read_b128 v[158:161], v226
	ds_read_b128 v[162:165], v209 offset:1152
	ds_read_b128 v[166:169], v209 offset:3456
	ds_read_b128 v[170:173], v208 offset:64
	ds_read_b128 v[174:177], v208 offset:2368
	ds_read_b128 v[178:181], v208 offset:4672
	ds_read_b128 v[182:185], v226 offset:64
	ds_read_b128 v[186:189], v209 offset:1216
	ds_read_b128 v[190:193], v209 offset:3520
	s_waitcnt lgkmcnt(6)
; #define MFMA16(a, b, c) __builtin_amdgcn_mfma_f32_16x16x32_bf16((a), (b), (c), 0, 0, 0)
; __device__ __forceinline__ void sample_out_block(LAS unsigned char* lds, const bf16_t* A, const bf16_t* Bt, int K, bf16_t* xb, float* sspart, int blk, int tid) {
;     ...
;         for (int k0 = 0; k0 < kq; k0 += 64) {
;             const int k1 = (k0 + 64 < kq) ? k0 + 64 : k0;
; #pragma unroll
;             for (int s = 0; s < 2; ++s) {
; #pragma unroll
;                 for (int ra = 0; ra < 2; ++ra) afn[s][ra] = *(const bf16x8*)(ap + (size_t)(16 * ra) * K + k1 + 32 * s);
; #pragma unroll
;                 for (int nt = 0; nt < 4; ++nt) bfn[s][nt] = *(const bf16x8*)(bp + (size_t)(16 * nt) * K + k1 + 32 * s);
;             }
; #pragma unroll
;             for (int s = 0; s < 2; ++s)
; #pragma unroll
;                 for (int ra = 0; ra < 2; ++ra)
; #pragma unroll
;                     for (int nt = 0; nt < 4; ++nt) acc[ra][nt] = MFMA16(af[s][ra], bf[s][nt], acc[ra][nt]);
; #pragma unroll
;             for (int s = 0; s < 2; ++s) {
; #pragma unroll
;                 for (int ra = 0; ra < 2; ++ra) af[s][ra] = afn[s][ra];
; #pragma unroll
;                 for (int nt = 0; nt < 4; ++nt) bf[s][nt] = bfn[s][nt];
;             }
;         }
	v_mfma_f32_16x16x32_bf16 v[8:11], v[146:149], v[154:157], v[8:11]
	v_mfma_f32_16x16x32_bf16 v[12:15], v[146:149], v[158:161], v[12:15]
	v_mfma_f32_16x16x32_bf16 v[16:19], v[146:149], v[162:165], v[16:19]
	v_mfma_f32_16x16x32_bf16 v[20:23], v[146:149], v[166:169], v[20:23]
	v_mfma_f32_16x16x32_bf16 v[24:27], v[150:153], v[154:157], v[24:27]
	v_mfma_f32_16x16x32_bf16 v[130:133], v[150:153], v[158:161], v[130:133]
	v_mfma_f32_16x16x32_bf16 v[134:137], v[150:153], v[162:165], v[134:137]
	v_mfma_f32_16x16x32_bf16 v[194:197], v[150:153], v[166:169], v[194:197]
	s_waitcnt lgkmcnt(0)
	v_mfma_f32_16x16x32_bf16 v[8:11], v[170:173], v[178:181], v[8:11]
	v_mfma_f32_16x16x32_bf16 v[12:15], v[170:173], v[182:185], v[12:15]
	v_mfma_f32_16x16x32_bf16 v[16:19], v[170:173], v[186:189], v[16:19]
	v_mfma_f32_16x16x32_bf16 v[20:23], v[170:173], v[190:193], v[20:23]
	v_mfma_f32_16x16x32_bf16 v[24:27], v[174:177], v[178:181], v[24:27]
	v_mfma_f32_16x16x32_bf16 v[130:133], v[174:177], v[182:185], v[130:133]
	v_mfma_f32_16x16x32_bf16 v[134:137], v[174:177], v[186:189], v[134:137]
	v_mfma_f32_16x16x32_bf16 v[194:197], v[174:177], v[190:193], v[194:197]
	s_waitcnt vmcnt(23)
	ds_write_b128 v206, v[82:85]
	s_waitcnt vmcnt(22)
	ds_write_b128 v206, v[86:89] offset:1152
	s_waitcnt vmcnt(21)
	ds_write_b128 v206, v[90:93] offset:2304
	s_waitcnt vmcnt(20)
	ds_write_b128 v206, v[94:97] offset:3456
	s_waitcnt vmcnt(19)
	ds_write_b128 v206, v[98:101] offset:4608
	s_waitcnt vmcnt(18)
	ds_write_b128 v206, v[102:105] offset:5760
	s_waitcnt vmcnt(17)
	ds_write_b128 v206, v[106:109] offset:6912
	s_waitcnt vmcnt(16)
	ds_write_b128 v207, v[110:113]
	s_waitcnt vmcnt(15)
	ds_write_b128 v207, v[114:117] offset:1152
	s_waitcnt vmcnt(14)
	ds_write_b128 v207, v[118:121] offset:2304
	s_waitcnt vmcnt(13)
	ds_write_b128 v207, v[122:125] offset:3456
	s_waitcnt vmcnt(12)
	ds_write_b128 v207, v[126:129] offset:4608
	global_load_dwordx4 v[82:85], v198, s[42:43] offset:640
	global_load_dwordx4 v[86:89], v199, s[42:43] offset:640
	global_load_dwordx4 v[90:93], v200, s[42:43] offset:640
	global_load_dwordx4 v[94:97], v201, s[42:43] offset:640
	global_load_dwordx4 v[98:101], v198, s[44:45] offset:640
	global_load_dwordx4 v[102:105], v199, s[44:45] offset:640
	global_load_dwordx4 v[106:109], v200, s[44:45] offset:640
	global_load_dwordx4 v[110:113], v201, s[44:45] offset:640
	global_load_dwordx4 v[114:117], v202, s[44:45] offset:640
	global_load_dwordx4 v[118:121], v203, s[44:45] offset:640
	global_load_dwordx4 v[122:125], v204, s[44:45] offset:640
	global_load_dwordx4 v[126:129], v205, s[44:45] offset:640
	ds_read_b128 v[146:149], v208 offset:0
	ds_read_b128 v[150:153], v208 offset:2304
	ds_read_b128 v[154:157], v208 offset:4608
	ds_read_b128 v[158:161], v226
	ds_read_b128 v[162:165], v209 offset:1152
	ds_read_b128 v[166:169], v209 offset:3456
	ds_read_b128 v[170:173], v208 offset:64
	ds_read_b128 v[174:177], v208 offset:2368
	ds_read_b128 v[178:181], v208 offset:4672
	ds_read_b128 v[182:185], v226 offset:64
	ds_read_b128 v[186:189], v209 offset:1216
	ds_read_b128 v[190:193], v209 offset:3520
	s_waitcnt lgkmcnt(6)
	v_mfma_f32_16x16x32_bf16 v[8:11], v[146:149], v[154:157], v[8:11]
	v_mfma_f32_16x16x32_bf16 v[12:15], v[146:149], v[158:161], v[12:15]
	v_mfma_f32_16x16x32_bf16 v[16:19], v[146:149], v[162:165], v[16:19]
	v_mfma_f32_16x16x32_bf16 v[20:23], v[146:149], v[166:169], v[20:23]
	v_mfma_f32_16x16x32_bf16 v[24:27], v[150:153], v[154:157], v[24:27]
	v_mfma_f32_16x16x32_bf16 v[130:133], v[150:153], v[158:161], v[130:133]
	v_mfma_f32_16x16x32_bf16 v[134:137], v[150:153], v[162:165], v[134:137]
	v_mfma_f32_16x16x32_bf16 v[194:197], v[150:153], v[166:169], v[194:197]
	s_waitcnt lgkmcnt(0)
	v_mfma_f32_16x16x32_bf16 v[8:11], v[170:173], v[178:181], v[8:11]
	v_mfma_f32_16x16x32_bf16 v[12:15], v[170:173], v[182:185], v[12:15]
	v_mfma_f32_16x16x32_bf16 v[16:19], v[170:173], v[186:189], v[16:19]
	v_mfma_f32_16x16x32_bf16 v[20:23], v[170:173], v[190:193], v[20:23]
	v_mfma_f32_16x16x32_bf16 v[24:27], v[174:177], v[178:181], v[24:27]
	v_mfma_f32_16x16x32_bf16 v[130:133], v[174:177], v[182:185], v[130:133]
	v_mfma_f32_16x16x32_bf16 v[134:137], v[174:177], v[186:189], v[134:137]
	v_mfma_f32_16x16x32_bf16 v[194:197], v[174:177], v[190:193], v[194:197]
	s_waitcnt vmcnt(23)
	ds_write_b128 v206, v[34:37]
	s_waitcnt vmcnt(22)
	ds_write_b128 v206, v[38:41] offset:1152
	s_waitcnt vmcnt(21)
	ds_write_b128 v206, v[42:45] offset:2304
	s_waitcnt vmcnt(20)
	ds_write_b128 v206, v[46:49] offset:3456
	s_waitcnt vmcnt(19)
	ds_write_b128 v206, v[50:53] offset:4608
	s_waitcnt vmcnt(18)
	ds_write_b128 v206, v[54:57] offset:5760
	s_waitcnt vmcnt(17)
	ds_write_b128 v206, v[58:61] offset:6912
	s_waitcnt vmcnt(16)
	ds_write_b128 v207, v[62:65]
	s_waitcnt vmcnt(15)
	ds_write_b128 v207, v[66:69] offset:1152
	s_waitcnt vmcnt(14)
	ds_write_b128 v207, v[70:73] offset:2304
	s_waitcnt vmcnt(13)
	ds_write_b128 v207, v[74:77] offset:3456
	s_waitcnt vmcnt(12)
	ds_write_b128 v207, v[78:81] offset:4608
	global_load_dwordx4 v[34:37], v198, s[42:43] offset:768
	global_load_dwordx4 v[38:41], v199, s[42:43] offset:768
	global_load_dwordx4 v[42:45], v200, s[42:43] offset:768
	global_load_dwordx4 v[46:49], v201, s[42:43] offset:768
	global_load_dwordx4 v[50:53], v198, s[44:45] offset:768
	global_load_dwordx4 v[54:57], v199, s[44:45] offset:768
	global_load_dwordx4 v[58:61], v200, s[44:45] offset:768
	global_load_dwordx4 v[62:65], v201, s[44:45] offset:768
	global_load_dwordx4 v[66:69], v202, s[44:45] offset:768
	global_load_dwordx4 v[70:73], v203, s[44:45] offset:768
	global_load_dwordx4 v[74:77], v204, s[44:45] offset:768
	global_load_dwordx4 v[78:81], v205, s[44:45] offset:768
	ds_read_b128 v[146:149], v208 offset:0
	ds_read_b128 v[150:153], v208 offset:2304
	ds_read_b128 v[154:157], v208 offset:4608
	ds_read_b128 v[158:161], v226
	ds_read_b128 v[162:165], v209 offset:1152
	ds_read_b128 v[166:169], v209 offset:3456
	ds_read_b128 v[170:173], v208 offset:64
	ds_read_b128 v[174:177], v208 offset:2368
	ds_read_b128 v[178:181], v208 offset:4672
	ds_read_b128 v[182:185], v226 offset:64
	ds_read_b128 v[186:189], v209 offset:1216
	ds_read_b128 v[190:193], v209 offset:3520
	s_waitcnt lgkmcnt(6)
; #define MFMA16(a, b, c) __builtin_amdgcn_mfma_f32_16x16x32_bf16((a), (b), (c), 0, 0, 0)
; __device__ __forceinline__ void sample_out_block(LAS unsigned char* lds, const bf16_t* A, const bf16_t* Bt, int K, bf16_t* xb, float* sspart, int blk, int tid) {
;     ...
;         for (int k0 = 0; k0 < kq; k0 += 64) {
;             const int k1 = (k0 + 64 < kq) ? k0 + 64 : k0;
; #pragma unroll
;             for (int s = 0; s < 2; ++s) {
; #pragma unroll
;                 for (int ra = 0; ra < 2; ++ra) afn[s][ra] = *(const bf16x8*)(ap + (size_t)(16 * ra) * K + k1 + 32 * s);
; #pragma unroll
;                 for (int nt = 0; nt < 4; ++nt) bfn[s][nt] = *(const bf16x8*)(bp + (size_t)(16 * nt) * K + k1 + 32 * s);
;             }
; #pragma unroll
;             for (int s = 0; s < 2; ++s)
; #pragma unroll
;                 for (int ra = 0; ra < 2; ++ra)
; #pragma unroll
;                     for (int nt = 0; nt < 4; ++nt) acc[ra][nt] = MFMA16(af[s][ra], bf[s][nt], acc[ra][nt]);
; #pragma unroll
;             for (int s = 0; s < 2; ++s) {
; #pragma unroll
;                 for (int ra = 0; ra < 2; ++ra) af[s][ra] = afn[s][ra];
; #pragma unroll
;                 for (int nt = 0; nt < 4; ++nt) bf[s][nt] = bfn[s][nt];
;             }
;         }
	v_mfma_f32_16x16x32_bf16 v[8:11], v[146:149], v[154:157], v[8:11]
	v_mfma_f32_16x16x32_bf16 v[12:15], v[146:149], v[158:161], v[12:15]
	v_mfma_f32_16x16x32_bf16 v[16:19], v[146:149], v[162:165], v[16:19]
	v_mfma_f32_16x16x32_bf16 v[20:23], v[146:149], v[166:169], v[20:23]
	v_mfma_f32_16x16x32_bf16 v[24:27], v[150:153], v[154:157], v[24:27]
	v_mfma_f32_16x16x32_bf16 v[130:133], v[150:153], v[158:161], v[130:133]
	v_mfma_f32_16x16x32_bf16 v[134:137], v[150:153], v[162:165], v[134:137]
	v_mfma_f32_16x16x32_bf16 v[194:197], v[150:153], v[166:169], v[194:197]
	s_waitcnt lgkmcnt(0)
	v_mfma_f32_16x16x32_bf16 v[8:11], v[170:173], v[178:181], v[8:11]
	v_mfma_f32_16x16x32_bf16 v[12:15], v[170:173], v[182:185], v[12:15]
	v_mfma_f32_16x16x32_bf16 v[16:19], v[170:173], v[186:189], v[16:19]
	v_mfma_f32_16x16x32_bf16 v[20:23], v[170:173], v[190:193], v[20:23]
	v_mfma_f32_16x16x32_bf16 v[24:27], v[174:177], v[178:181], v[24:27]
	v_mfma_f32_16x16x32_bf16 v[130:133], v[174:177], v[182:185], v[130:133]
	v_mfma_f32_16x16x32_bf16 v[134:137], v[174:177], v[186:189], v[134:137]
	v_mfma_f32_16x16x32_bf16 v[194:197], v[174:177], v[190:193], v[194:197]
	s_waitcnt vmcnt(23)
	ds_write_b128 v206, v[82:85]
	s_waitcnt vmcnt(22)
	ds_write_b128 v206, v[86:89] offset:1152
	s_waitcnt vmcnt(21)
	ds_write_b128 v206, v[90:93] offset:2304
	s_waitcnt vmcnt(20)
	ds_write_b128 v206, v[94:97] offset:3456
	s_waitcnt vmcnt(19)
	ds_write_b128 v206, v[98:101] offset:4608
	s_waitcnt vmcnt(18)
	ds_write_b128 v206, v[102:105] offset:5760
	s_waitcnt vmcnt(17)
	ds_write_b128 v206, v[106:109] offset:6912
	s_waitcnt vmcnt(16)
	ds_write_b128 v207, v[110:113]
	s_waitcnt vmcnt(15)
	ds_write_b128 v207, v[114:117] offset:1152
	s_waitcnt vmcnt(14)
	ds_write_b128 v207, v[118:121] offset:2304
	s_waitcnt vmcnt(13)
	ds_write_b128 v207, v[122:125] offset:3456
	s_waitcnt vmcnt(12)
	ds_write_b128 v207, v[126:129] offset:4608
	global_load_dwordx4 v[82:85], v198, s[42:43] offset:896
	global_load_dwordx4 v[86:89], v199, s[42:43] offset:896
	global_load_dwordx4 v[90:93], v200, s[42:43] offset:896
	global_load_dwordx4 v[94:97], v201, s[42:43] offset:896
	global_load_dwordx4 v[98:101], v198, s[44:45] offset:896
	global_load_dwordx4 v[102:105], v199, s[44:45] offset:896
	global_load_dwordx4 v[106:109], v200, s[44:45] offset:896
	global_load_dwordx4 v[110:113], v201, s[44:45] offset:896
	global_load_dwordx4 v[114:117], v202, s[44:45] offset:896
	global_load_dwordx4 v[118:121], v203, s[44:45] offset:896
	global_load_dwordx4 v[122:125], v204, s[44:45] offset:896
	global_load_dwordx4 v[126:129], v205, s[44:45] offset:896
	ds_read_b128 v[146:149], v208 offset:0
	ds_read_b128 v[150:153], v208 offset:2304
	ds_read_b128 v[154:157], v208 offset:4608
	ds_read_b128 v[158:161], v226
	ds_read_b128 v[162:165], v209 offset:1152
	ds_read_b128 v[166:169], v209 offset:3456
	ds_read_b128 v[170:173], v208 offset:64
	ds_read_b128 v[174:177], v208 offset:2368
	ds_read_b128 v[178:181], v208 offset:4672
	ds_read_b128 v[182:185], v226 offset:64
	ds_read_b128 v[186:189], v209 offset:1216
	ds_read_b128 v[190:193], v209 offset:3520
	s_waitcnt lgkmcnt(6)
	v_mfma_f32_16x16x32_bf16 v[8:11], v[146:149], v[154:157], v[8:11]
	v_mfma_f32_16x16x32_bf16 v[12:15], v[146:149], v[158:161], v[12:15]
	v_mfma_f32_16x16x32_bf16 v[16:19], v[146:149], v[162:165], v[16:19]
	v_mfma_f32_16x16x32_bf16 v[20:23], v[146:149], v[166:169], v[20:23]
	v_mfma_f32_16x16x32_bf16 v[24:27], v[150:153], v[154:157], v[24:27]
	v_mfma_f32_16x16x32_bf16 v[130:133], v[150:153], v[158:161], v[130:133]
	v_mfma_f32_16x16x32_bf16 v[134:137], v[150:153], v[162:165], v[134:137]
	v_mfma_f32_16x16x32_bf16 v[194:197], v[150:153], v[166:169], v[194:197]
	s_waitcnt lgkmcnt(0)
	v_mfma_f32_16x16x32_bf16 v[8:11], v[170:173], v[178:181], v[8:11]
	v_mfma_f32_16x16x32_bf16 v[12:15], v[170:173], v[182:185], v[12:15]
	v_mfma_f32_16x16x32_bf16 v[16:19], v[170:173], v[186:189], v[16:19]
	v_mfma_f32_16x16x32_bf16 v[20:23], v[170:173], v[190:193], v[20:23]
	v_mfma_f32_16x16x32_bf16 v[24:27], v[174:177], v[178:181], v[24:27]
	v_mfma_f32_16x16x32_bf16 v[130:133], v[174:177], v[182:185], v[130:133]
	v_mfma_f32_16x16x32_bf16 v[134:137], v[174:177], v[186:189], v[134:137]
	v_mfma_f32_16x16x32_bf16 v[194:197], v[174:177], v[190:193], v[194:197]
	s_waitcnt vmcnt(23)
	ds_write_b128 v206, v[34:37]
	s_waitcnt vmcnt(22)
	ds_write_b128 v206, v[38:41] offset:1152
	s_waitcnt vmcnt(21)
	ds_write_b128 v206, v[42:45] offset:2304
	s_waitcnt vmcnt(20)
	ds_write_b128 v206, v[46:49] offset:3456
	s_waitcnt vmcnt(19)
	ds_write_b128 v206, v[50:53] offset:4608
	s_waitcnt vmcnt(18)
	ds_write_b128 v206, v[54:57] offset:5760
	s_waitcnt vmcnt(17)
	ds_write_b128 v206, v[58:61] offset:6912
	s_waitcnt vmcnt(16)
	ds_write_b128 v207, v[62:65]
	s_waitcnt vmcnt(15)
	ds_write_b128 v207, v[66:69] offset:1152
	s_waitcnt vmcnt(14)
	ds_write_b128 v207, v[70:73] offset:2304
	s_waitcnt vmcnt(13)
	ds_write_b128 v207, v[74:77] offset:3456
	s_waitcnt vmcnt(12)
	ds_write_b128 v207, v[78:81] offset:4608
	ds_read_b128 v[146:149], v208 offset:0
	ds_read_b128 v[150:153], v208 offset:2304
	ds_read_b128 v[154:157], v208 offset:4608
	ds_read_b128 v[158:161], v226
	ds_read_b128 v[162:165], v209 offset:1152
	ds_read_b128 v[166:169], v209 offset:3456
	ds_read_b128 v[170:173], v208 offset:64
	ds_read_b128 v[174:177], v208 offset:2368
	ds_read_b128 v[178:181], v208 offset:4672
	ds_read_b128 v[182:185], v226 offset:64
	ds_read_b128 v[186:189], v209 offset:1216
	ds_read_b128 v[190:193], v209 offset:3520
	s_waitcnt lgkmcnt(6)
; #define LAS __attribute__((address_space(3)))
; #define MFMA16(a, b, c) __builtin_amdgcn_mfma_f32_16x16x32_bf16((a), (b), (c), 0, 0, 0)
; __device__ __forceinline__ float bf1(bf16_t h) { return __uint_as_float((unsigned)h << 16); }
; __device__ __forceinline__ bf16_t f2bf(float f) { return (bf16_t)(pk2(f, 0.f) & 0xffffu); }
; __device__ __forceinline__ void sample_out_block(LAS unsigned char* lds, const bf16_t* A, const bf16_t* Bt, int K, bf16_t* xb, float* sspart, int blk, int tid) {
;     ...
; #pragma unroll
;             for (int s = 0; s < 2; ++s)
; #pragma unroll
;                 for (int ra = 0; ra < 2; ++ra)
; #pragma unroll
;                     for (int nt = 0; nt < 4; ++nt) acc[ra][nt] = MFMA16(af[s][ra], bf[s][nt], acc[ra][nt]);
; #pragma unroll
;             for (int s = 0; s < 2; ++s) {
; #pragma unroll
;                 for (int ra = 0; ra < 2; ++ra) af[s][ra] = afn[s][ra];
; #pragma unroll
;                 for (int nt = 0; nt < 4; ++nt) bf[s][nt] = bfn[s][nt];
;             }
;         }
;     }
;     LAS f32x4* part = (LAS f32x4*)lds;
; #pragma unroll
;     for (int ra = 0; ra < 2; ++ra)
; #pragma unroll
;         for (int nt = 0; nt < 4; ++nt) part[(wave * 8 + ra * 4 + nt) * 64 + lane] = acc[ra][nt];
;     __syncthreads();
;     if (wave < 2) {
;         const int ra = wave;
;         f32x4 sum[4];
; #pragma unroll
;         for (int nt = 0; nt < 4; ++nt) {
;             sum[nt] = part[(0 * 8 + ra * 4 + nt) * 64 + lane];
; #pragma unroll
;             for (int w = 1; w < 8; ++w) sum[nt] += part[(w * 8 + ra * 4 + nt) * 64 + lane];
;         }
;         float ss[4] = {0.f, 0.f, 0.f, 0.f};
; #pragma unroll
;         for (int j = 0; j < 4; ++j)
; #pragma unroll
;             for (int nt = 0; nt < 4; ++nt) {
;                 bf16_t* xp = xb + (size_t)(r0 + 16 * ra + 4 * g + j) * 2048 + 64 * cg + 16 * nt + l15;
;                 const bf16_t nv = f2bf(bf1(*xp) + sum[nt][j]);
;                 *xp = nv; const float r = bf1(nv); ss[j] += r * r;
	v_mfma_f32_16x16x32_bf16 v[8:11], v[146:149], v[154:157], v[8:11]
	v_mfma_f32_16x16x32_bf16 v[12:15], v[146:149], v[158:161], v[12:15]
	v_mfma_f32_16x16x32_bf16 v[16:19], v[146:149], v[162:165], v[16:19]
	v_mfma_f32_16x16x32_bf16 v[20:23], v[146:149], v[166:169], v[20:23]
	v_mfma_f32_16x16x32_bf16 v[24:27], v[150:153], v[154:157], v[24:27]
	v_mfma_f32_16x16x32_bf16 v[130:133], v[150:153], v[158:161], v[130:133]
	v_mfma_f32_16x16x32_bf16 v[134:137], v[150:153], v[162:165], v[134:137]
	v_mfma_f32_16x16x32_bf16 v[194:197], v[150:153], v[166:169], v[194:197]
	s_waitcnt lgkmcnt(0)
	v_mfma_f32_16x16x32_bf16 v[8:11], v[170:173], v[178:181], v[8:11]
	v_mfma_f32_16x16x32_bf16 v[12:15], v[170:173], v[182:185], v[12:15]
	v_mfma_f32_16x16x32_bf16 v[16:19], v[170:173], v[186:189], v[16:19]
	v_mfma_f32_16x16x32_bf16 v[20:23], v[170:173], v[190:193], v[20:23]
	v_mfma_f32_16x16x32_bf16 v[24:27], v[174:177], v[178:181], v[24:27]
	v_mfma_f32_16x16x32_bf16 v[130:133], v[174:177], v[182:185], v[130:133]
	v_mfma_f32_16x16x32_bf16 v[134:137], v[174:177], v[186:189], v[134:137]
	v_mfma_f32_16x16x32_bf16 v[194:197], v[174:177], v[190:193], v[194:197]
	s_waitcnt vmcnt(11)
	ds_write_b128 v206, v[82:85]
	s_waitcnt vmcnt(10)
	ds_write_b128 v206, v[86:89] offset:1152
	s_waitcnt vmcnt(9)
	ds_write_b128 v206, v[90:93] offset:2304
	s_waitcnt vmcnt(8)
	ds_write_b128 v206, v[94:97] offset:3456
	s_waitcnt vmcnt(7)
	ds_write_b128 v206, v[98:101] offset:4608
	s_waitcnt vmcnt(6)
	ds_write_b128 v206, v[102:105] offset:5760
	s_waitcnt vmcnt(5)
	ds_write_b128 v206, v[106:109] offset:6912
	s_waitcnt vmcnt(4)
	ds_write_b128 v207, v[110:113]
	s_waitcnt vmcnt(3)
	ds_write_b128 v207, v[114:117] offset:1152
	s_waitcnt vmcnt(2)
	ds_write_b128 v207, v[118:121] offset:2304
	s_waitcnt vmcnt(1)
	ds_write_b128 v207, v[122:125] offset:3456
	s_waitcnt vmcnt(0)
	ds_write_b128 v207, v[126:129] offset:4608
	ds_read_b128 v[146:149], v208 offset:0
	ds_read_b128 v[150:153], v208 offset:2304
	ds_read_b128 v[154:157], v208 offset:4608
	ds_read_b128 v[158:161], v226
	ds_read_b128 v[162:165], v209 offset:1152
	ds_read_b128 v[166:169], v209 offset:3456
	ds_read_b128 v[170:173], v208 offset:64
	ds_read_b128 v[174:177], v208 offset:2368
	ds_read_b128 v[178:181], v208 offset:4672
	ds_read_b128 v[182:185], v226 offset:64
	ds_read_b128 v[186:189], v209 offset:1216
	ds_read_b128 v[190:193], v209 offset:3520
	s_waitcnt lgkmcnt(6)
	v_mfma_f32_16x16x32_bf16 v[8:11], v[146:149], v[154:157], v[8:11]
	v_mfma_f32_16x16x32_bf16 v[12:15], v[146:149], v[158:161], v[12:15]
	v_mfma_f32_16x16x32_bf16 v[16:19], v[146:149], v[162:165], v[16:19]
	v_mfma_f32_16x16x32_bf16 v[20:23], v[146:149], v[166:169], v[20:23]
	v_mfma_f32_16x16x32_bf16 v[24:27], v[150:153], v[154:157], v[24:27]
	v_mfma_f32_16x16x32_bf16 v[130:133], v[150:153], v[158:161], v[130:133]
	v_mfma_f32_16x16x32_bf16 v[134:137], v[150:153], v[162:165], v[134:137]
	v_mfma_f32_16x16x32_bf16 v[194:197], v[150:153], v[166:169], v[194:197]
	s_waitcnt lgkmcnt(0)
	v_mfma_f32_16x16x32_bf16 v[8:11], v[170:173], v[178:181], v[8:11]
	v_mfma_f32_16x16x32_bf16 v[12:15], v[170:173], v[182:185], v[12:15]
	v_mfma_f32_16x16x32_bf16 v[16:19], v[170:173], v[186:189], v[16:19]
	v_mfma_f32_16x16x32_bf16 v[20:23], v[170:173], v[190:193], v[20:23]
	v_mfma_f32_16x16x32_bf16 v[24:27], v[174:177], v[178:181], v[24:27]
	v_mfma_f32_16x16x32_bf16 v[130:133], v[174:177], v[182:185], v[130:133]
	v_mfma_f32_16x16x32_bf16 v[134:137], v[174:177], v[186:189], v[134:137]
	v_mfma_f32_16x16x32_bf16 v[194:197], v[174:177], v[190:193], v[194:197]
	s_nop 7
	s_nop 7
	ds_write_b128 v32, v[8:11]
	ds_write_b128 v32, v[12:15] offset:1024
	ds_write_b128 v32, v[16:19] offset:2048
	ds_write_b128 v32, v[20:23] offset:3072
	ds_write_b128 v32, v[24:27] offset:4096
	ds_write_b128 v32, v[130:133] offset:5120
	ds_write_b128 v32, v[134:137] offset:6144
	ds_write_b128 v32, v[194:197] offset:7168
	s_waitcnt lgkmcnt(0)
	s_barrier
	s_and_saveexec_b64 s[10:11], s[6:7]
	s_cbranch_execz .LBB0_541
	v_add_u32_e32 v170, s27, v31
	v_lshlrev_b32_e32 v170, 12, v170
	s_lshl_b32 s36, s35, 1
	v_add_u32_e32 v170, s36, v170
	v_mov_b32_e32 v171, 0
	s_mov_b64 s[38:39], 0x1000
	v_lshl_add_u64 v[162:163], v[6:7], 0, v[170:171]
	v_lshl_add_u64 v[164:165], v[162:163], 0, s[38:39]
	v_lshl_add_u64 v[166:167], v[164:165], 0, s[38:39]
	v_lshl_add_u64 v[168:169], v[166:167], 0, s[38:39]
	global_load_ushort v146, v[162:163], off
	global_load_ushort v147, v[162:163], off offset:32
	global_load_ushort v148, v[162:163], off offset:64
	global_load_ushort v149, v[162:163], off offset:96
	global_load_ushort v150, v[164:165], off
	global_load_ushort v151, v[164:165], off offset:32
	global_load_ushort v152, v[164:165], off offset:64
	global_load_ushort v153, v[164:165], off offset:96
	global_load_ushort v154, v[166:167], off
	global_load_ushort v155, v[166:167], off offset:32
	global_load_ushort v156, v[166:167], off offset:64
	global_load_ushort v157, v[166:167], off offset:96
	global_load_ushort v158, v[168:169], off
	global_load_ushort v159, v[168:169], off offset:32
	global_load_ushort v160, v[168:169], off offset:64
	global_load_ushort v161, v[168:169], off offset:96
	ds_read_b128 v[38:41], v33
	ds_read_b128 v[42:45], v33 offset:8192
	ds_read_b128 v[46:49], v33 offset:16384
	ds_read_b128 v[50:53], v33 offset:24576
	ds_read_b128 v[54:57], v33 offset:32768
	ds_read_b128 v[58:61], v33 offset:40960
	ds_read_b128 v[62:65], v33 offset:49152
	ds_read_b128 v[66:69], v33 offset:57344
	ds_read_b128 v[70:73], v33 offset:1024
	ds_read_b128 v[74:77], v33 offset:9216
	ds_read_b128 v[78:81], v33 offset:17408
	ds_read_b128 v[82:85], v33 offset:25600
	ds_read_b128 v[86:89], v33 offset:33792
	ds_read_b128 v[90:93], v33 offset:41984
	ds_read_b128 v[94:97], v33 offset:50176
	ds_read_b128 v[98:101], v33 offset:58368
	ds_read_b128 v[102:105], v33 offset:2048
	ds_read_b128 v[106:109], v33 offset:10240
	ds_read_b128 v[110:113], v33 offset:18432
	ds_read_b128 v[114:117], v33 offset:26624
	ds_read_b128 v[118:121], v33 offset:34816
	ds_read_b128 v[122:125], v33 offset:43008
	ds_read_b128 v[126:129], v33 offset:51200
	ds_read_b128 v[172:175], v33 offset:59392
	ds_read_b128 v[176:179], v33 offset:3072
	ds_read_b128 v[180:183], v33 offset:11264
	ds_read_b128 v[184:187], v33 offset:19456
	ds_read_b128 v[188:191], v33 offset:60416
	ds_read_b128 v[192:195], v33 offset:27648
	ds_read_b128 v[196:199], v33 offset:35840
	ds_read_b128 v[200:203], v33 offset:44032
	ds_read_b128 v[204:207], v33 offset:52224
	s_waitcnt lgkmcnt(0)
; __device__ __forceinline__ void sample_out_block(LAS unsigned char* lds, const bf16_t* A, const bf16_t* Bt, int K, bf16_t* xb, float* sspart, int blk, int tid) {
;     ...
;     if (wave < 2) {
;         const int ra = wave;
;         f32x4 sum[4];
; #pragma unroll
;         for (int nt = 0; nt < 4; ++nt) {
;             sum[nt] = part[(0 * 8 + ra * 4 + nt) * 64 + lane];
; #pragma unroll
;             for (int w = 1; w < 8; ++w) sum[nt] += part[(w * 8 + ra * 4 + nt) * 64 + lane];
;         }
	v_mov_b32_e32 v8, v38
	v_mov_b32_e32 v9, v39
	v_mov_b32_e32 v10, v40
	v_mov_b32_e32 v11, v41
	v_mov_b32_e32 v12, v42
	v_mov_b32_e32 v13, v43
	v_mov_b32_e32 v14, v44
	v_mov_b32_e32 v15, v45
	s_lshl_b32 s80, s35, 1
	v_lshl_add_u64 v[28:29], v[6:7], 0, s[80:81]
	s_lshl_b32 s12, s26, 2
	s_add_u32 s12, s22, s12
	s_waitcnt lgkmcnt(0)
	v_pk_add_f32 v[14:15], v[10:11], v[14:15]
	v_pk_add_f32 v[12:13], v[8:9], v[12:13]
	v_mov_b32_e32 v8, v46
	v_mov_b32_e32 v9, v47
	v_mov_b32_e32 v10, v48
	v_mov_b32_e32 v11, v49
	s_addc_u32 s13, s23, 0
	s_waitcnt lgkmcnt(0)
	v_pk_add_f32 v[14:15], v[14:15], v[10:11]
	v_pk_add_f32 v[12:13], v[12:13], v[8:9]
	v_mov_b32_e32 v8, v50
	v_mov_b32_e32 v9, v51
	v_mov_b32_e32 v10, v52
	v_mov_b32_e32 v11, v53
	s_waitcnt lgkmcnt(0)
	v_pk_add_f32 v[14:15], v[14:15], v[10:11]
	v_pk_add_f32 v[12:13], v[12:13], v[8:9]
	v_mov_b32_e32 v8, v54
	v_mov_b32_e32 v9, v55
	v_mov_b32_e32 v10, v56
	v_mov_b32_e32 v11, v57
	s_waitcnt lgkmcnt(0)
	v_pk_add_f32 v[14:15], v[14:15], v[10:11]
	v_pk_add_f32 v[12:13], v[12:13], v[8:9]
	v_mov_b32_e32 v8, v58
	v_mov_b32_e32 v9, v59
	v_mov_b32_e32 v10, v60
	v_mov_b32_e32 v11, v61
	s_waitcnt lgkmcnt(0)
	v_pk_add_f32 v[14:15], v[14:15], v[10:11]
	v_pk_add_f32 v[12:13], v[12:13], v[8:9]
	v_mov_b32_e32 v8, v62
	v_mov_b32_e32 v9, v63
	v_mov_b32_e32 v10, v64
	v_mov_b32_e32 v11, v65
	s_waitcnt lgkmcnt(0)
	v_pk_add_f32 v[14:15], v[14:15], v[10:11]
	v_pk_add_f32 v[16:17], v[12:13], v[8:9]
	v_mov_b32_e32 v8, v66
	v_mov_b32_e32 v9, v67
	v_mov_b32_e32 v10, v68
	v_mov_b32_e32 v11, v69
	s_waitcnt lgkmcnt(0)
	v_pk_add_f32 v[12:13], v[14:15], v[10:11]
	v_pk_add_f32 v[20:21], v[16:17], v[8:9]
	v_mov_b32_e32 v8, v70
	v_mov_b32_e32 v9, v71
	v_mov_b32_e32 v10, v72
	v_mov_b32_e32 v11, v73
	v_mov_b32_e32 v14, v74
	v_mov_b32_e32 v15, v75
	v_mov_b32_e32 v16, v76
	v_mov_b32_e32 v17, v77
	s_waitcnt lgkmcnt(0)
	v_pk_add_f32 v[16:17], v[10:11], v[16:17]
	v_pk_add_f32 v[14:15], v[8:9], v[14:15]
	v_mov_b32_e32 v8, v78
	v_mov_b32_e32 v9, v79
	v_mov_b32_e32 v10, v80
	v_mov_b32_e32 v11, v81
	s_waitcnt lgkmcnt(0)
	v_pk_add_f32 v[16:17], v[16:17], v[10:11]
	v_pk_add_f32 v[14:15], v[14:15], v[8:9]
	v_mov_b32_e32 v8, v82
	v_mov_b32_e32 v9, v83
	v_mov_b32_e32 v10, v84
	v_mov_b32_e32 v11, v85
	s_waitcnt lgkmcnt(0)
	v_pk_add_f32 v[16:17], v[16:17], v[10:11]
	v_pk_add_f32 v[14:15], v[14:15], v[8:9]
	v_mov_b32_e32 v8, v86
	v_mov_b32_e32 v9, v87
	v_mov_b32_e32 v10, v88
	v_mov_b32_e32 v11, v89
	s_waitcnt lgkmcnt(0)
	v_pk_add_f32 v[16:17], v[16:17], v[10:11]
	v_pk_add_f32 v[14:15], v[14:15], v[8:9]
	v_mov_b32_e32 v8, v90
	v_mov_b32_e32 v9, v91
	v_mov_b32_e32 v10, v92
	v_mov_b32_e32 v11, v93
	s_waitcnt lgkmcnt(0)
	v_pk_add_f32 v[16:17], v[16:17], v[10:11]
	v_pk_add_f32 v[14:15], v[14:15], v[8:9]
	v_mov_b32_e32 v8, v94
	v_mov_b32_e32 v9, v95
	v_mov_b32_e32 v10, v96
	v_mov_b32_e32 v11, v97
	s_waitcnt lgkmcnt(0)
	v_pk_add_f32 v[16:17], v[16:17], v[10:11]
	v_pk_add_f32 v[14:15], v[14:15], v[8:9]
	v_mov_b32_e32 v8, v98
	v_mov_b32_e32 v9, v99
	v_mov_b32_e32 v10, v100
	v_mov_b32_e32 v11, v101
	s_waitcnt lgkmcnt(0)
	v_pk_add_f32 v[18:19], v[16:17], v[10:11]
	v_pk_add_f32 v[26:27], v[14:15], v[8:9]
	v_mov_b32_e32 v8, v102
	v_mov_b32_e32 v9, v103
	v_mov_b32_e32 v10, v104
	v_mov_b32_e32 v11, v105
	v_mov_b32_e32 v14, v106
	v_mov_b32_e32 v15, v107
	v_mov_b32_e32 v16, v108
	v_mov_b32_e32 v17, v109
	s_waitcnt lgkmcnt(0)
	v_pk_add_f32 v[16:17], v[10:11], v[16:17]
	v_pk_add_f32 v[14:15], v[8:9], v[14:15]
	v_mov_b32_e32 v8, v110
	v_mov_b32_e32 v9, v111
	v_mov_b32_e32 v10, v112
	v_mov_b32_e32 v11, v113
	s_waitcnt lgkmcnt(0)
	v_pk_add_f32 v[16:17], v[16:17], v[10:11]
	v_pk_add_f32 v[14:15], v[14:15], v[8:9]
	v_mov_b32_e32 v8, v114
	v_mov_b32_e32 v9, v115
	v_mov_b32_e32 v10, v116
	v_mov_b32_e32 v11, v117
	s_waitcnt lgkmcnt(0)
	v_pk_add_f32 v[16:17], v[16:17], v[10:11]
	v_pk_add_f32 v[14:15], v[14:15], v[8:9]
	v_mov_b32_e32 v8, v118
	v_mov_b32_e32 v9, v119
	v_mov_b32_e32 v10, v120
	v_mov_b32_e32 v11, v121
	s_waitcnt lgkmcnt(0)
	v_pk_add_f32 v[16:17], v[16:17], v[10:11]
	v_pk_add_f32 v[14:15], v[14:15], v[8:9]
	v_mov_b32_e32 v8, v122
	v_mov_b32_e32 v9, v123
	v_mov_b32_e32 v10, v124
	v_mov_b32_e32 v11, v125
	s_waitcnt lgkmcnt(0)
	v_pk_add_f32 v[16:17], v[16:17], v[10:11]
	v_pk_add_f32 v[14:15], v[14:15], v[8:9]
	v_mov_b32_e32 v8, v126
	v_mov_b32_e32 v9, v127
	v_mov_b32_e32 v10, v128
	v_mov_b32_e32 v11, v129
	s_waitcnt lgkmcnt(0)
	v_pk_add_f32 v[16:17], v[16:17], v[10:11]
	v_pk_add_f32 v[14:15], v[14:15], v[8:9]
	v_mov_b32_e32 v8, v172
	v_mov_b32_e32 v9, v173
	v_mov_b32_e32 v10, v174
	v_mov_b32_e32 v11, v175
	s_waitcnt lgkmcnt(0)
	v_pk_add_f32 v[16:17], v[16:17], v[10:11]
	v_pk_add_f32 v[24:25], v[14:15], v[8:9]
	v_mov_b32_e32 v8, v176
	v_mov_b32_e32 v9, v177
	v_mov_b32_e32 v10, v178
	v_mov_b32_e32 v11, v179
	v_mov_b32_e32 v34, v180
	v_mov_b32_e32 v35, v181
	v_mov_b32_e32 v36, v182
	v_mov_b32_e32 v37, v183
	s_waitcnt lgkmcnt(0)
	v_pk_add_f32 v[14:15], v[10:11], v[36:37]
	v_pk_add_f32 v[22:23], v[8:9], v[34:35]
	v_mov_b32_e32 v8, v184
	v_mov_b32_e32 v9, v185
	v_mov_b32_e32 v10, v186
	v_mov_b32_e32 v11, v187
	v_mov_b32_e32 v34, v188
	v_mov_b32_e32 v35, v189
	v_mov_b32_e32 v36, v190
	v_mov_b32_e32 v37, v191
	s_waitcnt lgkmcnt(1)
	v_pk_add_f32 v[14:15], v[14:15], v[10:11]
	v_pk_add_f32 v[22:23], v[22:23], v[8:9]
	v_mov_b32_e32 v8, v192
	v_mov_b32_e32 v9, v193
	v_mov_b32_e32 v10, v194
	v_mov_b32_e32 v11, v195
	s_waitcnt lgkmcnt(0)
; __device__ __forceinline__ float bf1(bf16_t h) { return __uint_as_float((unsigned)h << 16); }
; __device__ __forceinline__ bf16_t f2bf(float f) { return (bf16_t)(pk2(f, 0.f) & 0xffffu); }
; __device__ __forceinline__ void sample_out_block(LAS unsigned char* lds, const bf16_t* A, const bf16_t* Bt, int K, bf16_t* xb, float* sspart, int blk, int tid) {
;     ...
;         for (int nt = 0; nt < 4; ++nt) {
;             sum[nt] = part[(0 * 8 + ra * 4 + nt) * 64 + lane];
; #pragma unroll
;             for (int w = 1; w < 8; ++w) sum[nt] += part[(w * 8 + ra * 4 + nt) * 64 + lane];
;         }
;         float ss[4] = {0.f, 0.f, 0.f, 0.f};
; #pragma unroll
;         for (int j = 0; j < 4; ++j)
; #pragma unroll
;             for (int nt = 0; nt < 4; ++nt) {
;                 bf16_t* xp = xb + (size_t)(r0 + 16 * ra + 4 * g + j) * 2048 + 64 * cg + 16 * nt + l15;
;                 const bf16_t nv = f2bf(bf1(*xp) + sum[nt][j]);
;                 *xp = nv; const float r = bf1(nv); ss[j] += r * r;
;             }
; #pragma unroll
;         for (int j = 0; j < 4; ++j) {
;             float s = ss[j];
;             s += __shfl_xor(s, 1); s += __shfl_xor(s, 2); s += __shfl_xor(s, 4); s += __shfl_xor(s, 8);
;             if (l15 == 0) sspart[(size_t)(r0 + 16 * ra + 4 * g + j) * 32 + cg] = s;
;         }
	v_pk_add_f32 v[14:15], v[14:15], v[10:11]
	v_pk_add_f32 v[22:23], v[22:23], v[8:9]
	v_mov_b32_e32 v8, v196
	v_mov_b32_e32 v9, v197
	v_mov_b32_e32 v10, v198
	v_mov_b32_e32 v11, v199
	s_waitcnt lgkmcnt(0)
	v_pk_add_f32 v[14:15], v[14:15], v[10:11]
	v_pk_add_f32 v[22:23], v[22:23], v[8:9]
	v_mov_b32_e32 v8, v200
	v_mov_b32_e32 v9, v201
	v_mov_b32_e32 v10, v202
	v_mov_b32_e32 v11, v203
	s_waitcnt lgkmcnt(0)
	v_pk_add_f32 v[14:15], v[14:15], v[10:11]
	v_pk_add_f32 v[22:23], v[22:23], v[8:9]
	v_mov_b32_e32 v8, v204
	v_mov_b32_e32 v9, v205
	v_mov_b32_e32 v10, v206
	v_mov_b32_e32 v11, v207
	s_waitcnt lgkmcnt(0)
	v_pk_add_f32 v[10:11], v[14:15], v[10:11]
	v_pk_add_f32 v[14:15], v[22:23], v[8:9]
	v_pk_add_f32 v[8:9], v[10:11], v[36:37]
	v_add_u32_e32 v10, s27, v31
	v_ashrrev_i32_e32 v11, 31, v10
	v_pk_add_f32 v[22:23], v[14:15], v[34:35]
	v_lshlrev_b64 v[14:15], 12, v[10:11]
	v_lshl_add_u64 v[14:15], v[28:29], 0, v[14:15]
	s_waitcnt vmcnt(0)
	v_mov_b32_e32 v0, v146
	v_lshlrev_b32_e32 v0, 16, v0
	v_add_f32_e32 v0, v20, v0
	v_cvt_pk_bf16_f32 v0, v0, s0
	global_store_short v[14:15], v0, off
	v_lshlrev_b32_e32 v20, 16, v0
	v_mov_b32_e32 v0, v147
	v_lshlrev_b32_e32 v0, 16, v0
	v_add_f32_e32 v0, v26, v0
	v_cvt_pk_bf16_f32 v0, v0, s0
	global_store_short v[14:15], v0, off offset:32
	v_lshlrev_b32_e32 v0, 16, v0
	v_mul_f32_e32 v0, v0, v0
	v_fmac_f32_e32 v0, v20, v20
	v_mov_b32_e32 v20, v148
	v_lshlrev_b32_e32 v20, 16, v20
	v_add_f32_e32 v20, v24, v20
	v_cvt_pk_bf16_f32 v20, v20, s0
	global_store_short v[14:15], v20, off offset:64
	v_lshlrev_b32_e32 v20, 16, v20
	v_fmac_f32_e32 v0, v20, v20
	v_mov_b32_e32 v20, v149
	v_lshlrev_b32_e32 v20, 16, v20
	v_add_f32_e32 v20, v22, v20
	v_cvt_pk_bf16_f32 v20, v20, s0
	global_store_short v[14:15], v20, off offset:96
	v_lshlrev_b32_e32 v14, 16, v20
	v_fmac_f32_e32 v0, v14, v14
	v_or_b32_e32 v14, 1, v10
	v_ashrrev_i32_e32 v15, 31, v14
	v_lshlrev_b64 v[34:35], 12, v[14:15]
	v_lshl_add_u64 v[36:37], v[28:29], 0, v[34:35]
	v_mov_b32_e32 v20, v150
	v_lshlrev_b32_e32 v20, 16, v20
	v_add_f32_e32 v20, v21, v20
	v_cvt_pk_bf16_f32 v26, v20, s0
	v_mov_b32_e32 v20, v151
	v_lshlrev_b32_e32 v20, 16, v20
	v_add_f32_e32 v20, v27, v20
	v_cvt_pk_bf16_f32 v27, v20, s0
	v_mov_b32_e32 v20, v152
	v_lshlrev_b32_e32 v20, 16, v20
	v_add_f32_e32 v20, v25, v20
	v_cvt_pk_bf16_f32 v34, v20, s0
	v_mov_b32_e32 v20, v153
	v_lshlrev_b32_e32 v20, 16, v20
	v_add_f32_e32 v20, v23, v20
	v_cvt_pk_bf16_f32 v35, v20, s0
	v_or_b32_e32 v20, 2, v10
	v_ashrrev_i32_e32 v21, 31, v20
	v_lshlrev_b64 v[22:23], 12, v[20:21]
	v_lshl_add_u64 v[22:23], v[28:29], 0, v[22:23]
	v_mov_b32_e32 v24, v154
	v_lshlrev_b32_e32 v24, 16, v24
	v_add_f32_e32 v12, v12, v24
	v_mov_b32_e32 v24, v155
	v_cvt_pk_bf16_f32 v12, v12, s0
	global_store_short v[22:23], v12, off
	global_store_short v[36:37], v26, off
	global_store_short v[36:37], v27, off offset:32
	global_store_short v[36:37], v34, off offset:64
	global_store_short v[36:37], v35, off offset:96
	v_xor_b32_e32 v36, 8, v215
	s_waitcnt vmcnt(5)
	v_lshlrev_b32_e32 v24, 16, v24
	v_add_f32_e32 v18, v18, v24
	v_mov_b32_e32 v24, v156
	v_cvt_pk_bf16_f32 v18, v18, s0
	global_store_short v[22:23], v18, off offset:32
	s_waitcnt vmcnt(1)
	v_lshlrev_b32_e32 v24, 16, v24
	v_add_f32_e32 v16, v16, v24
	v_mov_b32_e32 v24, v157
	v_cvt_pk_bf16_f32 v16, v16, s0
	global_store_short v[22:23], v16, off offset:64
	s_waitcnt vmcnt(1)
	v_lshlrev_b32_e32 v24, 16, v24
	v_add_f32_e32 v8, v8, v24
	v_cvt_pk_bf16_f32 v8, v8, s0
	global_store_short v[22:23], v8, off offset:96
	v_or_b32_e32 v22, 3, v10
	v_ashrrev_i32_e32 v23, 31, v22
	v_lshlrev_b64 v[24:25], 12, v[22:23]
	v_lshl_add_u64 v[24:25], v[28:29], 0, v[24:25]
	v_mov_b32_e32 v28, v158
	v_lshlrev_b32_e32 v28, 16, v28
	v_add_f32_e32 v13, v13, v28
	v_mov_b32_e32 v28, v159
	v_cvt_pk_bf16_f32 v13, v13, s0
	global_store_short v[24:25], v13, off
	s_waitcnt vmcnt(1)
	v_lshlrev_b32_e32 v28, 16, v28
	v_add_f32_e32 v19, v19, v28
	v_mov_b32_e32 v28, v160
	v_cvt_pk_bf16_f32 v19, v19, s0
	global_store_short v[24:25], v19, off offset:32
	s_waitcnt vmcnt(1)
	v_lshlrev_b32_e32 v28, 16, v28
	v_add_f32_e32 v17, v17, v28
	v_mov_b32_e32 v28, v161
	v_cvt_pk_bf16_f32 v17, v17, s0
	global_store_short v[24:25], v17, off offset:64
	s_waitcnt vmcnt(1)
	v_lshlrev_b32_e32 v28, 16, v28
	v_add_f32_e32 v9, v9, v28
	v_cvt_pk_bf16_f32 v9, v9, s0
	global_store_short v[24:25], v9, off offset:96
	v_and_b32_e32 v25, 64, v215
	v_xor_b32_e32 v24, 1, v215
	v_add_u32_e32 v29, 64, v25
	v_cmp_lt_i32_e32 vcc, v24, v29
	v_xor_b32_e32 v25, 2, v215
	v_xor_b32_e32 v28, 4, v215
	v_cndmask_b32_e32 v24, v215, v24, vcc
	v_cmp_lt_i32_e32 vcc, v25, v29
	v_lshlrev_b32_e32 v24, 2, v24
	s_nop 0
	v_cndmask_b32_e32 v25, v215, v25, vcc
	v_cmp_lt_i32_e32 vcc, v28, v29
	v_lshlrev_b32_e32 v25, 2, v25
	s_nop 0
	v_cndmask_b32_e32 v28, v215, v28, vcc
	v_cmp_lt_i32_e32 vcc, v36, v29
	v_lshlrev_b32_e32 v28, 2, v28
	s_nop 0
	v_cndmask_b32_e32 v29, v215, v36, vcc
	ds_bpermute_b32 v36, v24, v0
	v_lshlrev_b32_e32 v29, 2, v29
	s_waitcnt lgkmcnt(0)
	v_add_f32_e32 v0, v0, v36
	ds_bpermute_b32 v36, v25, v0
	s_waitcnt lgkmcnt(0)
	v_add_f32_e32 v0, v0, v36
	ds_bpermute_b32 v36, v28, v0
	s_waitcnt lgkmcnt(0)
	v_add_f32_e32 v0, v0, v36
	ds_bpermute_b32 v36, v29, v0
	s_and_saveexec_b64 s[26:27], s[8:9]
	s_cbranch_execz .LBB0_545
	v_lshlrev_b64 v[10:11], 7, v[10:11]
	v_lshl_add_u64 v[10:11], s[12:13], 0, v[10:11]
	s_waitcnt lgkmcnt(0)
	v_add_f32_e32 v0, v0, v36
	global_store_dword v[10:11], v0, off

; #define MFMA16(a, b, c) __builtin_amdgcn_mfma_f32_16x16x32_bf16((a), (b), (c), 0, 0, 0)
; __device__ __forceinline__ void sample_out_block(LAS unsigned char* lds, const bf16_t* A, const bf16_t* Bt, int K, bf16_t* xb, float* sspart, int blk, int tid) {
;     const int wave = tid >> 6, lane = tid & 63, l15 = lane & 15, g = lane >> 4;
;     const int rt = blk >> 5, cg = blk & 31, r0 = T_P + 32 * rt;
;     const int kq = K >> 3;
;     f32x4 acc[2][4];
; #pragma unroll
;     for (int ra = 0; ra < 2; ++ra)
; #pragma unroll
;         for (int nt = 0; nt < 4; ++nt) acc[ra][nt] = (f32x4){0.f, 0.f, 0.f, 0.f};
;     {
;         const bf16_t* ap = A + (size_t)(r0 + l15) * K + wave * kq + 8 * g;
;         const bf16_t* bp = Bt + (size_t)(64 * cg + l15) * K + wave * kq + 8 * g;
;         bf16x8 af[2][2], bf[2][4], afn[2][2], bfn[2][4];
; #pragma unroll
;         for (int s = 0; s < 2; ++s) {
; #pragma unroll
;             for (int ra = 0; ra < 2; ++ra) af[s][ra] = *(const bf16x8*)(ap + (size_t)(16 * ra) * K + 32 * s);
; #pragma unroll
;             for (int nt = 0; nt < 4; ++nt) bf[s][nt] = *(const bf16x8*)(bp + (size_t)(16 * nt) * K + 32 * s);
;         }
;         for (int k0 = 0; k0 < kq; k0 += 64) {
;             const int k1 = (k0 + 64 < kq) ? k0 + 64 : k0;
; #pragma unroll
;             for (int s = 0; s < 2; ++s) {
; #pragma unroll
;                 for (int ra = 0; ra < 2; ++ra) afn[s][ra] = *(const bf16x8*)(ap + (size_t)(16 * ra) * K + k1 + 32 * s);
; #pragma unroll
;                 for (int nt = 0; nt < 4; ++nt) bfn[s][nt] = *(const bf16x8*)(bp + (size_t)(16 * nt) * K + k1 + 32 * s);
;             }
; #pragma unroll
;             for (int s = 0; s < 2; ++s)
; #pragma unroll
;                 for (int ra = 0; ra < 2; ++ra)
; #pragma unroll
;                     for (int nt = 0; nt < 4; ++nt) acc[ra][nt] = MFMA16(af[s][ra], bf[s][nt], acc[ra][nt]);
.LBB0_1165:
	s_and_b32 s21, s26, 0xffffffe0
	s_addk_i32 s21, 0x2000
	s_and_b32 s20, s26, 31
	v_or_b32_e32 v8, s21, v30
	v_ashrrev_i32_e32 v9, 31, v8
	s_lshl_b32 s27, s20, 6
	v_lshlrev_b64 v[8:9], 12, v[8:9]
	v_or_b32_e32 v0, s27, v30
	v_lshl_add_u64 v[10:11], v[2:3], 0, v[8:9]
	v_lshlrev_b32_e32 v0, 12, v0
	v_lshl_add_u64 v[16:17], v[4:5], 0, v[0:1]
	v_add_co_u32_e32 v8, vcc, 0x10000, v10
	s_mov_b64 s[8:9], vcc
	v_add_co_u32_e32 v12, vcc, 0x10000, v16
	v_readfirstlane_b32 s36, v139
	s_lshr_b32 s36, s36, 6
	s_and_b32 s37, s26, 0xffffffe0
	s_addk_i32 s37, 0x2000
	s_and_b32 s38, s26, 31
	s_lshl_b32 s38, s38, 6
	s_lshl_b32 s39, s37, 12
	s_mul_i32 s40, s36, 0x200
	s_add_u32 s42, s18, s39
	s_addc_u32 s43, s19, 0
	s_add_u32 s42, s42, s40
	s_addc_u32 s43, s43, 0
	s_lshl_b32 s41, s24, 1
	s_lshl_b32 s39, s38, 12
	s_add_u32 s44, s22, s41
	s_addc_u32 s45, s23, 0
	s_add_u32 s44, s44, s39
	s_addc_u32 s45, s45, 0
	s_add_u32 s44, s44, s40
	s_addc_u32 s45, s45, 0
	v_lshrrev_b32_e32 v227, 3, v215
	v_and_b32_e32 v228, 7, v215
	v_lshlrev_b32_e32 v198, 12, v227
	v_lshl_add_u32 v198, v228, 4, v198
	v_add_u32_e32 v199, 0x8000, v198
	v_add_u32_e32 v200, 0x10000, v198
	v_add_u32_e32 v201, 0x18000, v198
	v_add_u32_e32 v202, 0x20000, v198
	v_add_u32_e32 v203, 0x28000, v198
	v_add_u32_e32 v204, 0x30000, v198
	v_add_u32_e32 v205, 0x38000, v198
	s_lshl_b32 s46, s36, 13
	s_mul_i32 s47, s36, 0x1800
	s_add_i32 s47, s47, 0x10000
	v_mul_u32_u24_e32 v206, 0x90, v227
	v_lshl_add_u32 v206, v228, 4, v206
	v_add_u32_e32 v207, s47, v206
	v_add_u32_e32 v206, s46, v206
	v_and_b32_e32 v227, 15, v215
	v_lshrrev_b32_e32 v228, 4, v215
	v_mul_u32_u24_e32 v208, 0x90, v227
	v_lshl_add_u32 v208, v228, 4, v208
	v_add_u32_e32 v209, s47, v208
	v_add_u32_e32 v208, s46, v208
	v_add_u32_e32 v226, 0x1b00, v208
	v_subrev_u32_e32 v228, 0x480, v209
	v_cmp_gt_u32_e32 vcc, 8, v227
	v_cndmask_b32_e32 v226, v228, v226, vcc
	global_load_dwordx4 v[34:37], v198, s[42:43]
	global_load_dwordx4 v[38:41], v199, s[42:43]
	global_load_dwordx4 v[42:45], v200, s[42:43]
	global_load_dwordx4 v[46:49], v201, s[42:43]
	global_load_dwordx4 v[50:53], v198, s[44:45]
	global_load_dwordx4 v[54:57], v199, s[44:45]
	global_load_dwordx4 v[58:61], v200, s[44:45]
	global_load_dwordx4 v[62:65], v201, s[44:45]
	global_load_dwordx4 v[66:69], v202, s[44:45]
	global_load_dwordx4 v[70:73], v203, s[44:45]
	global_load_dwordx4 v[74:77], v204, s[44:45]
	global_load_dwordx4 v[78:81], v205, s[44:45]
	global_load_dwordx4 v[82:85], v198, s[42:43] offset:128
	global_load_dwordx4 v[86:89], v199, s[42:43] offset:128
	global_load_dwordx4 v[90:93], v200, s[42:43] offset:128
	global_load_dwordx4 v[94:97], v201, s[42:43] offset:128
	global_load_dwordx4 v[98:101], v198, s[44:45] offset:128
	global_load_dwordx4 v[102:105], v199, s[44:45] offset:128
	global_load_dwordx4 v[106:109], v200, s[44:45] offset:128
	global_load_dwordx4 v[110:113], v201, s[44:45] offset:128
	global_load_dwordx4 v[114:117], v202, s[44:45] offset:128
	global_load_dwordx4 v[118:121], v203, s[44:45] offset:128
	global_load_dwordx4 v[122:125], v204, s[44:45] offset:128
	global_load_dwordx4 v[126:129], v205, s[44:45] offset:128
	s_waitcnt vmcnt(23)
	ds_write_b128 v206, v[34:37]
	s_waitcnt vmcnt(22)
	ds_write_b128 v206, v[38:41] offset:1152
	s_waitcnt vmcnt(21)
	ds_write_b128 v206, v[42:45] offset:2304
	s_waitcnt vmcnt(20)
	ds_write_b128 v206, v[46:49] offset:3456
	s_waitcnt vmcnt(19)
	ds_write_b128 v206, v[50:53] offset:4608
	s_waitcnt vmcnt(18)
	ds_write_b128 v206, v[54:57] offset:5760
	s_waitcnt vmcnt(17)
	ds_write_b128 v206, v[58:61] offset:6912
	s_waitcnt vmcnt(16)
	ds_write_b128 v207, v[62:65]
	s_waitcnt vmcnt(15)
	ds_write_b128 v207, v[66:69] offset:1152
	s_waitcnt vmcnt(14)
	ds_write_b128 v207, v[70:73] offset:2304
	s_waitcnt vmcnt(13)
	ds_write_b128 v207, v[74:77] offset:3456
	s_waitcnt vmcnt(12)
	ds_write_b128 v207, v[78:81] offset:4608
	global_load_dwordx4 v[34:37], v198, s[42:43] offset:256
	global_load_dwordx4 v[38:41], v199, s[42:43] offset:256
	global_load_dwordx4 v[42:45], v200, s[42:43] offset:256
	global_load_dwordx4 v[46:49], v201, s[42:43] offset:256
	global_load_dwordx4 v[50:53], v198, s[44:45] offset:256
	global_load_dwordx4 v[54:57], v199, s[44:45] offset:256
	global_load_dwordx4 v[58:61], v200, s[44:45] offset:256
	global_load_dwordx4 v[62:65], v201, s[44:45] offset:256
	global_load_dwordx4 v[66:69], v202, s[44:45] offset:256
	global_load_dwordx4 v[70:73], v203, s[44:45] offset:256
	global_load_dwordx4 v[74:77], v204, s[44:45] offset:256
	global_load_dwordx4 v[78:81], v205, s[44:45] offset:256
	ds_read_b128 v[146:149], v208 offset:0
	ds_read_b128 v[150:153], v208 offset:2304
	ds_read_b128 v[154:157], v208 offset:4608
	ds_read_b128 v[158:161], v226
	ds_read_b128 v[162:165], v209 offset:1152
	ds_read_b128 v[166:169], v209 offset:3456
	ds_read_b128 v[170:173], v208 offset:64
	ds_read_b128 v[174:177], v208 offset:2368
	ds_read_b128 v[178:181], v208 offset:4672
	ds_read_b128 v[182:185], v226 offset:64
	ds_read_b128 v[186:189], v209 offset:1216
	ds_read_b128 v[190:193], v209 offset:3520
	s_waitcnt lgkmcnt(6)
	v_mfma_f32_16x16x32_bf16 v[8:11], v[146:149], v[154:157], 0
	v_mfma_f32_16x16x32_bf16 v[12:15], v[146:149], v[158:161], 0
	v_mfma_f32_16x16x32_bf16 v[16:19], v[146:149], v[162:165], 0
	v_mfma_f32_16x16x32_bf16 v[20:23], v[146:149], v[166:169], 0
	v_mfma_f32_16x16x32_bf16 v[24:27], v[150:153], v[154:157], 0
	v_mfma_f32_16x16x32_bf16 v[130:133], v[150:153], v[158:161], 0
	v_mfma_f32_16x16x32_bf16 v[134:137], v[150:153], v[162:165], 0
	v_mfma_f32_16x16x32_bf16 v[194:197], v[150:153], v[166:169], 0
	s_waitcnt lgkmcnt(0)
; #define MFMA16(a, b, c) __builtin_amdgcn_mfma_f32_16x16x32_bf16((a), (b), (c), 0, 0, 0)
; __device__ __forceinline__ void sample_out_block(LAS unsigned char* lds, const bf16_t* A, const bf16_t* Bt, int K, bf16_t* xb, float* sspart, int blk, int tid) {
;     ...
;         for (int k0 = 0; k0 < kq; k0 += 64) {
;             const int k1 = (k0 + 64 < kq) ? k0 + 64 : k0;
; #pragma unroll
;             for (int s = 0; s < 2; ++s) {
; #pragma unroll
;                 for (int ra = 0; ra < 2; ++ra) afn[s][ra] = *(const bf16x8*)(ap + (size_t)(16 * ra) * K + k1 + 32 * s);
; #pragma unroll
;                 for (int nt = 0; nt < 4; ++nt) bfn[s][nt] = *(const bf16x8*)(bp + (size_t)(16 * nt) * K + k1 + 32 * s);
;             }
; #pragma unroll
;             for (int s = 0; s < 2; ++s)
; #pragma unroll
;                 for (int ra = 0; ra < 2; ++ra)
; #pragma unroll
;                     for (int nt = 0; nt < 4; ++nt) acc[ra][nt] = MFMA16(af[s][ra], bf[s][nt], acc[ra][nt]);
; #pragma unroll
;             for (int s = 0; s < 2; ++s) {
; #pragma unroll
;                 for (int ra = 0; ra < 2; ++ra) af[s][ra] = afn[s][ra];
; #pragma unroll
;                 for (int nt = 0; nt < 4; ++nt) bf[s][nt] = bfn[s][nt];
;             }
;         }
	v_mfma_f32_16x16x32_bf16 v[8:11], v[170:173], v[178:181], v[8:11]
	v_mfma_f32_16x16x32_bf16 v[12:15], v[170:173], v[182:185], v[12:15]
	v_mfma_f32_16x16x32_bf16 v[16:19], v[170:173], v[186:189], v[16:19]
	v_mfma_f32_16x16x32_bf16 v[20:23], v[170:173], v[190:193], v[20:23]
	v_mfma_f32_16x16x32_bf16 v[24:27], v[174:177], v[178:181], v[24:27]
	v_mfma_f32_16x16x32_bf16 v[130:133], v[174:177], v[182:185], v[130:133]
	v_mfma_f32_16x16x32_bf16 v[134:137], v[174:177], v[186:189], v[134:137]
	v_mfma_f32_16x16x32_bf16 v[194:197], v[174:177], v[190:193], v[194:197]
	s_waitcnt vmcnt(23)
	ds_write_b128 v206, v[82:85]
	s_waitcnt vmcnt(22)
	ds_write_b128 v206, v[86:89] offset:1152
	s_waitcnt vmcnt(21)
	ds_write_b128 v206, v[90:93] offset:2304
	s_waitcnt vmcnt(20)
	ds_write_b128 v206, v[94:97] offset:3456
	s_waitcnt vmcnt(19)
	ds_write_b128 v206, v[98:101] offset:4608
	s_waitcnt vmcnt(18)
	ds_write_b128 v206, v[102:105] offset:5760
	s_waitcnt vmcnt(17)
	ds_write_b128 v206, v[106:109] offset:6912
	s_waitcnt vmcnt(16)
	ds_write_b128 v207, v[110:113]
	s_waitcnt vmcnt(15)
	ds_write_b128 v207, v[114:117] offset:1152
	s_waitcnt vmcnt(14)
	ds_write_b128 v207, v[118:121] offset:2304
	s_waitcnt vmcnt(13)
	ds_write_b128 v207, v[122:125] offset:3456
	s_waitcnt vmcnt(12)
	ds_write_b128 v207, v[126:129] offset:4608
	global_load_dwordx4 v[82:85], v198, s[42:43] offset:384
	global_load_dwordx4 v[86:89], v199, s[42:43] offset:384
	global_load_dwordx4 v[90:93], v200, s[42:43] offset:384
	global_load_dwordx4 v[94:97], v201, s[42:43] offset:384
	global_load_dwordx4 v[98:101], v198, s[44:45] offset:384
	global_load_dwordx4 v[102:105], v199, s[44:45] offset:384
	global_load_dwordx4 v[106:109], v200, s[44:45] offset:384
	global_load_dwordx4 v[110:113], v201, s[44:45] offset:384
	global_load_dwordx4 v[114:117], v202, s[44:45] offset:384
	global_load_dwordx4 v[118:121], v203, s[44:45] offset:384
	global_load_dwordx4 v[122:125], v204, s[44:45] offset:384
	global_load_dwordx4 v[126:129], v205, s[44:45] offset:384
	ds_read_b128 v[146:149], v208 offset:0
	ds_read_b128 v[150:153], v208 offset:2304
	ds_read_b128 v[154:157], v208 offset:4608
	ds_read_b128 v[158:161], v226
	ds_read_b128 v[162:165], v209 offset:1152
	ds_read_b128 v[166:169], v209 offset:3456
	ds_read_b128 v[170:173], v208 offset:64
	ds_read_b128 v[174:177], v208 offset:2368
	ds_read_b128 v[178:181], v208 offset:4672
	ds_read_b128 v[182:185], v226 offset:64
	ds_read_b128 v[186:189], v209 offset:1216
	ds_read_b128 v[190:193], v209 offset:3520
	s_waitcnt lgkmcnt(6)
	v_mfma_f32_16x16x32_bf16 v[8:11], v[146:149], v[154:157], v[8:11]
	v_mfma_f32_16x16x32_bf16 v[12:15], v[146:149], v[158:161], v[12:15]
	v_mfma_f32_16x16x32_bf16 v[16:19], v[146:149], v[162:165], v[16:19]
	v_mfma_f32_16x16x32_bf16 v[20:23], v[146:149], v[166:169], v[20:23]
	v_mfma_f32_16x16x32_bf16 v[24:27], v[150:153], v[154:157], v[24:27]
	v_mfma_f32_16x16x32_bf16 v[130:133], v[150:153], v[158:161], v[130:133]
	v_mfma_f32_16x16x32_bf16 v[134:137], v[150:153], v[162:165], v[134:137]
	v_mfma_f32_16x16x32_bf16 v[194:197], v[150:153], v[166:169], v[194:197]
	s_waitcnt lgkmcnt(0)
	v_mfma_f32_16x16x32_bf16 v[8:11], v[170:173], v[178:181], v[8:11]
	v_mfma_f32_16x16x32_bf16 v[12:15], v[170:173], v[182:185], v[12:15]
	v_mfma_f32_16x16x32_bf16 v[16:19], v[170:173], v[186:189], v[16:19]
	v_mfma_f32_16x16x32_bf16 v[20:23], v[170:173], v[190:193], v[20:23]
	v_mfma_f32_16x16x32_bf16 v[24:27], v[174:177], v[178:181], v[24:27]
	v_mfma_f32_16x16x32_bf16 v[130:133], v[174:177], v[182:185], v[130:133]
	v_mfma_f32_16x16x32_bf16 v[134:137], v[174:177], v[186:189], v[134:137]
	v_mfma_f32_16x16x32_bf16 v[194:197], v[174:177], v[190:193], v[194:197]
	s_waitcnt vmcnt(23)
	ds_write_b128 v206, v[34:37]
	s_waitcnt vmcnt(22)
	ds_write_b128 v206, v[38:41] offset:1152
	s_waitcnt vmcnt(21)
	ds_write_b128 v206, v[42:45] offset:2304
	s_waitcnt vmcnt(20)
	ds_write_b128 v206, v[46:49] offset:3456
	s_waitcnt vmcnt(19)
	ds_write_b128 v206, v[50:53] offset:4608
	s_waitcnt vmcnt(18)
	ds_write_b128 v206, v[54:57] offset:5760
	s_waitcnt vmcnt(17)
	ds_write_b128 v206, v[58:61] offset:6912
	s_waitcnt vmcnt(16)
	ds_write_b128 v207, v[62:65]
	s_waitcnt vmcnt(15)
	ds_write_b128 v207, v[66:69] offset:1152
	s_waitcnt vmcnt(14)
	ds_write_b128 v207, v[70:73] offset:2304
	s_waitcnt vmcnt(13)
	ds_write_b128 v207, v[74:77] offset:3456
	s_waitcnt vmcnt(12)
	ds_write_b128 v207, v[78:81] offset:4608
	ds_read_b128 v[146:149], v208 offset:0
	ds_read_b128 v[150:153], v208 offset:2304
	ds_read_b128 v[154:157], v208 offset:4608
	ds_read_b128 v[158:161], v226
	ds_read_b128 v[162:165], v209 offset:1152
	ds_read_b128 v[166:169], v209 offset:3456
	ds_read_b128 v[170:173], v208 offset:64
	ds_read_b128 v[174:177], v208 offset:2368
	ds_read_b128 v[178:181], v208 offset:4672
	ds_read_b128 v[182:185], v226 offset:64
	ds_read_b128 v[186:189], v209 offset:1216
	ds_read_b128 v[190:193], v209 offset:3520
	s_waitcnt lgkmcnt(6)
	v_mfma_f32_16x16x32_bf16 v[8:11], v[146:149], v[154:157], v[8:11]
	v_mfma_f32_16x16x32_bf16 v[12:15], v[146:149], v[158:161], v[12:15]
	v_mfma_f32_16x16x32_bf16 v[16:19], v[146:149], v[162:165], v[16:19]
	v_mfma_f32_16x16x32_bf16 v[20:23], v[146:149], v[166:169], v[20:23]
	v_mfma_f32_16x16x32_bf16 v[24:27], v[150:153], v[154:157], v[24:27]
	v_mfma_f32_16x16x32_bf16 v[130:133], v[150:153], v[158:161], v[130:133]
	v_mfma_f32_16x16x32_bf16 v[134:137], v[150:153], v[162:165], v[134:137]
	v_mfma_f32_16x16x32_bf16 v[194:197], v[150:153], v[166:169], v[194:197]
	s_waitcnt lgkmcnt(0)
; #define LAS __attribute__((address_space(3)))
; #define MFMA16(a, b, c) __builtin_amdgcn_mfma_f32_16x16x32_bf16((a), (b), (c), 0, 0, 0)
; __device__ __forceinline__ float bf1(bf16_t h) { return __uint_as_float((unsigned)h << 16); }
; __device__ __forceinline__ bf16_t f2bf(float f) { return (bf16_t)(pk2(f, 0.f) & 0xffffu); }
; __device__ __forceinline__ void sample_out_block(LAS unsigned char* lds, const bf16_t* A, const bf16_t* Bt, int K, bf16_t* xb, float* sspart, int blk, int tid) {
;     ...
; #pragma unroll
;             for (int s = 0; s < 2; ++s)
; #pragma unroll
;                 for (int ra = 0; ra < 2; ++ra)
; #pragma unroll
;                     for (int nt = 0; nt < 4; ++nt) acc[ra][nt] = MFMA16(af[s][ra], bf[s][nt], acc[ra][nt]);
; #pragma unroll
;             for (int s = 0; s < 2; ++s) {
; #pragma unroll
;                 for (int ra = 0; ra < 2; ++ra) af[s][ra] = afn[s][ra];
; #pragma unroll
;                 for (int nt = 0; nt < 4; ++nt) bf[s][nt] = bfn[s][nt];
;             }
;         }
;     }
;     LAS f32x4* part = (LAS f32x4*)lds;
; #pragma unroll
;     for (int ra = 0; ra < 2; ++ra)
; #pragma unroll
;         for (int nt = 0; nt < 4; ++nt) part[(wave * 8 + ra * 4 + nt) * 64 + lane] = acc[ra][nt];
;     __syncthreads();
;     if (wave < 2) {
;         const int ra = wave;
;         f32x4 sum[4];
; #pragma unroll
;         for (int nt = 0; nt < 4; ++nt) {
;             sum[nt] = part[(0 * 8 + ra * 4 + nt) * 64 + lane];
; #pragma unroll
;             for (int w = 1; w < 8; ++w) sum[nt] += part[(w * 8 + ra * 4 + nt) * 64 + lane];
;         }
;         float ss[4] = {0.f, 0.f, 0.f, 0.f};
; #pragma unroll
;         for (int j = 0; j < 4; ++j)
; #pragma unroll
;             for (int nt = 0; nt < 4; ++nt) {
;                 bf16_t* xp = xb + (size_t)(r0 + 16 * ra + 4 * g + j) * 2048 + 64 * cg + 16 * nt + l15;
;                 const bf16_t nv = f2bf(bf1(*xp) + sum[nt][j]);
	v_mfma_f32_16x16x32_bf16 v[8:11], v[170:173], v[178:181], v[8:11]
	v_mfma_f32_16x16x32_bf16 v[12:15], v[170:173], v[182:185], v[12:15]
	v_mfma_f32_16x16x32_bf16 v[16:19], v[170:173], v[186:189], v[16:19]
	v_mfma_f32_16x16x32_bf16 v[20:23], v[170:173], v[190:193], v[20:23]
	v_mfma_f32_16x16x32_bf16 v[24:27], v[174:177], v[178:181], v[24:27]
	v_mfma_f32_16x16x32_bf16 v[130:133], v[174:177], v[182:185], v[130:133]
	v_mfma_f32_16x16x32_bf16 v[134:137], v[174:177], v[186:189], v[134:137]
	v_mfma_f32_16x16x32_bf16 v[194:197], v[174:177], v[190:193], v[194:197]
	s_waitcnt vmcnt(11)
	ds_write_b128 v206, v[82:85]
	s_waitcnt vmcnt(10)
	ds_write_b128 v206, v[86:89] offset:1152
	s_waitcnt vmcnt(9)
	ds_write_b128 v206, v[90:93] offset:2304
	s_waitcnt vmcnt(8)
	ds_write_b128 v206, v[94:97] offset:3456
	s_waitcnt vmcnt(7)
	ds_write_b128 v206, v[98:101] offset:4608
	s_waitcnt vmcnt(6)
	ds_write_b128 v206, v[102:105] offset:5760
	s_waitcnt vmcnt(5)
	ds_write_b128 v206, v[106:109] offset:6912
	s_waitcnt vmcnt(4)
	ds_write_b128 v207, v[110:113]
	s_waitcnt vmcnt(3)
	ds_write_b128 v207, v[114:117] offset:1152
	s_waitcnt vmcnt(2)
	ds_write_b128 v207, v[118:121] offset:2304
	s_waitcnt vmcnt(1)
	ds_write_b128 v207, v[122:125] offset:3456
	s_waitcnt vmcnt(0)
	ds_write_b128 v207, v[126:129] offset:4608
	ds_read_b128 v[146:149], v208 offset:0
	ds_read_b128 v[150:153], v208 offset:2304
	ds_read_b128 v[154:157], v208 offset:4608
	ds_read_b128 v[158:161], v226
	ds_read_b128 v[162:165], v209 offset:1152
	ds_read_b128 v[166:169], v209 offset:3456
	ds_read_b128 v[170:173], v208 offset:64
	ds_read_b128 v[174:177], v208 offset:2368
	ds_read_b128 v[178:181], v208 offset:4672
	ds_read_b128 v[182:185], v226 offset:64
	ds_read_b128 v[186:189], v209 offset:1216
	ds_read_b128 v[190:193], v209 offset:3520
	s_waitcnt lgkmcnt(6)
	v_mfma_f32_16x16x32_bf16 v[8:11], v[146:149], v[154:157], v[8:11]
	v_mfma_f32_16x16x32_bf16 v[12:15], v[146:149], v[158:161], v[12:15]
	v_mfma_f32_16x16x32_bf16 v[16:19], v[146:149], v[162:165], v[16:19]
	v_mfma_f32_16x16x32_bf16 v[20:23], v[146:149], v[166:169], v[20:23]
	v_mfma_f32_16x16x32_bf16 v[24:27], v[150:153], v[154:157], v[24:27]
	v_mfma_f32_16x16x32_bf16 v[130:133], v[150:153], v[158:161], v[130:133]
	v_mfma_f32_16x16x32_bf16 v[134:137], v[150:153], v[162:165], v[134:137]
	v_mfma_f32_16x16x32_bf16 v[194:197], v[150:153], v[166:169], v[194:197]
	s_waitcnt lgkmcnt(0)
	v_mfma_f32_16x16x32_bf16 v[8:11], v[170:173], v[178:181], v[8:11]
	v_mfma_f32_16x16x32_bf16 v[12:15], v[170:173], v[182:185], v[12:15]
	v_mfma_f32_16x16x32_bf16 v[16:19], v[170:173], v[186:189], v[16:19]
	v_mfma_f32_16x16x32_bf16 v[20:23], v[170:173], v[190:193], v[20:23]
	v_mfma_f32_16x16x32_bf16 v[24:27], v[174:177], v[178:181], v[24:27]
	v_mfma_f32_16x16x32_bf16 v[130:133], v[174:177], v[182:185], v[130:133]
	v_mfma_f32_16x16x32_bf16 v[134:137], v[174:177], v[186:189], v[134:137]
	v_mfma_f32_16x16x32_bf16 v[194:197], v[174:177], v[190:193], v[194:197]
	s_nop 7
	s_nop 7
	ds_write_b128 v32, v[8:11]
	ds_write_b128 v32, v[12:15] offset:1024
	ds_write_b128 v32, v[16:19] offset:2048
	ds_write_b128 v32, v[20:23] offset:3072
	ds_write_b128 v32, v[24:27] offset:4096
	ds_write_b128 v32, v[130:133] offset:5120
	ds_write_b128 v32, v[134:137] offset:6144
	ds_write_b128 v32, v[194:197] offset:7168
	s_waitcnt lgkmcnt(0)
	s_barrier
	s_and_saveexec_b64 s[8:9], s[4:5]
	s_cbranch_execz .LBB0_1164
	v_add_u32_e32 v170, s21, v31
	v_lshlrev_b32_e32 v170, 12, v170
	s_lshl_b32 s36, s27, 1
	v_add_u32_e32 v170, s36, v170
	v_mov_b32_e32 v171, 0
	s_mov_b64 s[38:39], 0x1000
	v_lshl_add_u64 v[162:163], v[6:7], 0, v[170:171]
	v_lshl_add_u64 v[164:165], v[162:163], 0, s[38:39]
	v_lshl_add_u64 v[166:167], v[164:165], 0, s[38:39]
	v_lshl_add_u64 v[168:169], v[166:167], 0, s[38:39]
	global_load_ushort v146, v[162:163], off
	global_load_ushort v147, v[162:163], off offset:32
	global_load_ushort v148, v[162:163], off offset:64
	global_load_ushort v149, v[162:163], off offset:96
	global_load_ushort v150, v[164:165], off
	global_load_ushort v151, v[164:165], off offset:32
	global_load_ushort v152, v[164:165], off offset:64
	global_load_ushort v153, v[164:165], off offset:96
	global_load_ushort v154, v[166:167], off
	global_load_ushort v155, v[166:167], off offset:32
	global_load_ushort v156, v[166:167], off offset:64
	global_load_ushort v157, v[166:167], off offset:96
	global_load_ushort v158, v[168:169], off
	global_load_ushort v159, v[168:169], off offset:32
	global_load_ushort v160, v[168:169], off offset:64
	global_load_ushort v161, v[168:169], off offset:96
	ds_read_b128 v[38:41], v33
	ds_read_b128 v[42:45], v33 offset:8192
	ds_read_b128 v[46:49], v33 offset:16384
	ds_read_b128 v[50:53], v33 offset:24576
	ds_read_b128 v[54:57], v33 offset:32768
	ds_read_b128 v[58:61], v33 offset:40960
	ds_read_b128 v[62:65], v33 offset:49152
	ds_read_b128 v[66:69], v33 offset:57344
	ds_read_b128 v[70:73], v33 offset:1024
	ds_read_b128 v[74:77], v33 offset:9216
	ds_read_b128 v[78:81], v33 offset:17408
	ds_read_b128 v[82:85], v33 offset:25600
	ds_read_b128 v[86:89], v33 offset:33792
	ds_read_b128 v[90:93], v33 offset:41984
	ds_read_b128 v[94:97], v33 offset:50176
	ds_read_b128 v[98:101], v33 offset:58368
	ds_read_b128 v[102:105], v33 offset:2048
	ds_read_b128 v[106:109], v33 offset:10240
	ds_read_b128 v[110:113], v33 offset:18432
	ds_read_b128 v[114:117], v33 offset:26624
	ds_read_b128 v[118:121], v33 offset:34816
	ds_read_b128 v[122:125], v33 offset:43008
	ds_read_b128 v[126:129], v33 offset:51200
	ds_read_b128 v[172:175], v33 offset:59392
	ds_read_b128 v[176:179], v33 offset:3072
	ds_read_b128 v[180:183], v33 offset:11264
	ds_read_b128 v[184:187], v33 offset:19456
	ds_read_b128 v[188:191], v33 offset:60416
	ds_read_b128 v[192:195], v33 offset:27648
	ds_read_b128 v[196:199], v33 offset:35840
	ds_read_b128 v[200:203], v33 offset:44032
	ds_read_b128 v[204:207], v33 offset:52224
	s_waitcnt lgkmcnt(0)
; __device__ __forceinline__ void sample_out_block(LAS unsigned char* lds, const bf16_t* A, const bf16_t* Bt, int K, bf16_t* xb, float* sspart, int blk, int tid) {
;     ...
;     if (wave < 2) {
;         const int ra = wave;
;         f32x4 sum[4];
; #pragma unroll
;         for (int nt = 0; nt < 4; ++nt) {
;             sum[nt] = part[(0 * 8 + ra * 4 + nt) * 64 + lane];
; #pragma unroll
;             for (int w = 1; w < 8; ++w) sum[nt] += part[(w * 8 + ra * 4 + nt) * 64 + lane];
;         }
	v_mov_b32_e32 v8, v38
	v_mov_b32_e32 v9, v39
	v_mov_b32_e32 v10, v40
	v_mov_b32_e32 v11, v41
	v_mov_b32_e32 v12, v42
	v_mov_b32_e32 v13, v43
	v_mov_b32_e32 v14, v44
	v_mov_b32_e32 v15, v45
	s_lshl_b32 s80, s27, 1
	v_lshl_add_u64 v[28:29], v[6:7], 0, s[80:81]
	s_lshl_b32 s10, s20, 2
	s_add_u32 s10, s16, s10
	s_waitcnt lgkmcnt(0)
	v_pk_add_f32 v[14:15], v[10:11], v[14:15]
	v_pk_add_f32 v[12:13], v[8:9], v[12:13]
	v_mov_b32_e32 v8, v46
	v_mov_b32_e32 v9, v47
	v_mov_b32_e32 v10, v48
	v_mov_b32_e32 v11, v49
	s_addc_u32 s11, s17, 0
	s_waitcnt lgkmcnt(0)
	v_pk_add_f32 v[14:15], v[14:15], v[10:11]
	v_pk_add_f32 v[12:13], v[12:13], v[8:9]
	v_mov_b32_e32 v8, v50
	v_mov_b32_e32 v9, v51
	v_mov_b32_e32 v10, v52
	v_mov_b32_e32 v11, v53
	s_waitcnt lgkmcnt(0)
	v_pk_add_f32 v[14:15], v[14:15], v[10:11]
	v_pk_add_f32 v[12:13], v[12:13], v[8:9]
	v_mov_b32_e32 v8, v54
	v_mov_b32_e32 v9, v55
	v_mov_b32_e32 v10, v56
	v_mov_b32_e32 v11, v57
	s_waitcnt lgkmcnt(0)
	v_pk_add_f32 v[14:15], v[14:15], v[10:11]
	v_pk_add_f32 v[12:13], v[12:13], v[8:9]
	v_mov_b32_e32 v8, v58
	v_mov_b32_e32 v9, v59
	v_mov_b32_e32 v10, v60
	v_mov_b32_e32 v11, v61
	s_waitcnt lgkmcnt(0)
	v_pk_add_f32 v[14:15], v[14:15], v[10:11]
	v_pk_add_f32 v[12:13], v[12:13], v[8:9]
	v_mov_b32_e32 v8, v62
	v_mov_b32_e32 v9, v63
	v_mov_b32_e32 v10, v64
	v_mov_b32_e32 v11, v65
	s_waitcnt lgkmcnt(0)
	v_pk_add_f32 v[14:15], v[14:15], v[10:11]
	v_pk_add_f32 v[16:17], v[12:13], v[8:9]
	v_mov_b32_e32 v8, v66
	v_mov_b32_e32 v9, v67
	v_mov_b32_e32 v10, v68
	v_mov_b32_e32 v11, v69
	s_waitcnt lgkmcnt(0)
	v_pk_add_f32 v[12:13], v[14:15], v[10:11]
	v_pk_add_f32 v[20:21], v[16:17], v[8:9]
	v_mov_b32_e32 v8, v70
	v_mov_b32_e32 v9, v71
	v_mov_b32_e32 v10, v72
	v_mov_b32_e32 v11, v73
	v_mov_b32_e32 v14, v74
	v_mov_b32_e32 v15, v75
	v_mov_b32_e32 v16, v76
	v_mov_b32_e32 v17, v77
	s_waitcnt lgkmcnt(0)
	v_pk_add_f32 v[16:17], v[10:11], v[16:17]
	v_pk_add_f32 v[14:15], v[8:9], v[14:15]
	v_mov_b32_e32 v8, v78
	v_mov_b32_e32 v9, v79
	v_mov_b32_e32 v10, v80
	v_mov_b32_e32 v11, v81
	s_waitcnt lgkmcnt(0)
	v_pk_add_f32 v[16:17], v[16:17], v[10:11]
	v_pk_add_f32 v[14:15], v[14:15], v[8:9]
	v_mov_b32_e32 v8, v82
	v_mov_b32_e32 v9, v83
	v_mov_b32_e32 v10, v84
	v_mov_b32_e32 v11, v85
	s_waitcnt lgkmcnt(0)
	v_pk_add_f32 v[16:17], v[16:17], v[10:11]
	v_pk_add_f32 v[14:15], v[14:15], v[8:9]
	v_mov_b32_e32 v8, v86
	v_mov_b32_e32 v9, v87
	v_mov_b32_e32 v10, v88
	v_mov_b32_e32 v11, v89
	s_waitcnt lgkmcnt(0)
	v_pk_add_f32 v[16:17], v[16:17], v[10:11]
	v_pk_add_f32 v[14:15], v[14:15], v[8:9]
	v_mov_b32_e32 v8, v90
	v_mov_b32_e32 v9, v91
	v_mov_b32_e32 v10, v92
	v_mov_b32_e32 v11, v93
	s_waitcnt lgkmcnt(0)
	v_pk_add_f32 v[16:17], v[16:17], v[10:11]
	v_pk_add_f32 v[14:15], v[14:15], v[8:9]
	v_mov_b32_e32 v8, v94
	v_mov_b32_e32 v9, v95
	v_mov_b32_e32 v10, v96
	v_mov_b32_e32 v11, v97
	s_waitcnt lgkmcnt(0)
	v_pk_add_f32 v[16:17], v[16:17], v[10:11]
	v_pk_add_f32 v[14:15], v[14:15], v[8:9]
	v_mov_b32_e32 v8, v98
	v_mov_b32_e32 v9, v99
	v_mov_b32_e32 v10, v100
	v_mov_b32_e32 v11, v101
	s_waitcnt lgkmcnt(0)
	v_pk_add_f32 v[18:19], v[16:17], v[10:11]
	v_pk_add_f32 v[26:27], v[14:15], v[8:9]
	v_mov_b32_e32 v8, v102
	v_mov_b32_e32 v9, v103
	v_mov_b32_e32 v10, v104
	v_mov_b32_e32 v11, v105
	v_mov_b32_e32 v14, v106
	v_mov_b32_e32 v15, v107
	v_mov_b32_e32 v16, v108
	v_mov_b32_e32 v17, v109
	s_waitcnt lgkmcnt(0)
	v_pk_add_f32 v[16:17], v[10:11], v[16:17]
	v_pk_add_f32 v[14:15], v[8:9], v[14:15]
	v_mov_b32_e32 v8, v110
	v_mov_b32_e32 v9, v111
	v_mov_b32_e32 v10, v112
	v_mov_b32_e32 v11, v113
	s_waitcnt lgkmcnt(0)
	v_pk_add_f32 v[16:17], v[16:17], v[10:11]
	v_pk_add_f32 v[14:15], v[14:15], v[8:9]
	v_mov_b32_e32 v8, v114
	v_mov_b32_e32 v9, v115
	v_mov_b32_e32 v10, v116
	v_mov_b32_e32 v11, v117
	s_waitcnt lgkmcnt(0)
	v_pk_add_f32 v[16:17], v[16:17], v[10:11]
	v_pk_add_f32 v[14:15], v[14:15], v[8:9]
	v_mov_b32_e32 v8, v118
	v_mov_b32_e32 v9, v119
	v_mov_b32_e32 v10, v120
	v_mov_b32_e32 v11, v121
	s_waitcnt lgkmcnt(0)
	v_pk_add_f32 v[16:17], v[16:17], v[10:11]
	v_pk_add_f32 v[14:15], v[14:15], v[8:9]
	v_mov_b32_e32 v8, v122
	v_mov_b32_e32 v9, v123
	v_mov_b32_e32 v10, v124
	v_mov_b32_e32 v11, v125
	s_waitcnt lgkmcnt(0)
	v_pk_add_f32 v[16:17], v[16:17], v[10:11]
	v_pk_add_f32 v[14:15], v[14:15], v[8:9]
	v_mov_b32_e32 v8, v126
	v_mov_b32_e32 v9, v127
	v_mov_b32_e32 v10, v128
	v_mov_b32_e32 v11, v129
	s_waitcnt lgkmcnt(0)
	v_pk_add_f32 v[16:17], v[16:17], v[10:11]
	v_pk_add_f32 v[14:15], v[14:15], v[8:9]
	v_mov_b32_e32 v8, v172
	v_mov_b32_e32 v9, v173
	v_mov_b32_e32 v10, v174
	v_mov_b32_e32 v11, v175
	s_waitcnt lgkmcnt(0)
	v_pk_add_f32 v[16:17], v[16:17], v[10:11]
	v_pk_add_f32 v[24:25], v[14:15], v[8:9]
	v_mov_b32_e32 v8, v176
	v_mov_b32_e32 v9, v177
	v_mov_b32_e32 v10, v178
	v_mov_b32_e32 v11, v179
	v_mov_b32_e32 v34, v180
	v_mov_b32_e32 v35, v181
	v_mov_b32_e32 v36, v182
	v_mov_b32_e32 v37, v183
	s_waitcnt lgkmcnt(0)
	v_pk_add_f32 v[14:15], v[10:11], v[36:37]
	v_pk_add_f32 v[22:23], v[8:9], v[34:35]
	v_mov_b32_e32 v8, v184
	v_mov_b32_e32 v9, v185
	v_mov_b32_e32 v10, v186
	v_mov_b32_e32 v11, v187
	v_mov_b32_e32 v34, v188
	v_mov_b32_e32 v35, v189
	v_mov_b32_e32 v36, v190
	v_mov_b32_e32 v37, v191
	s_waitcnt lgkmcnt(1)
	v_pk_add_f32 v[14:15], v[14:15], v[10:11]
	v_pk_add_f32 v[22:23], v[22:23], v[8:9]
	v_mov_b32_e32 v8, v192
	v_mov_b32_e32 v9, v193
	v_mov_b32_e32 v10, v194
	v_mov_b32_e32 v11, v195
	s_waitcnt lgkmcnt(0)
; __device__ __forceinline__ float bf1(bf16_t h) { return __uint_as_float((unsigned)h << 16); }
; __device__ __forceinline__ bf16_t f2bf(float f) { return (bf16_t)(pk2(f, 0.f) & 0xffffu); }
; __device__ __forceinline__ void sample_out_block(LAS unsigned char* lds, const bf16_t* A, const bf16_t* Bt, int K, bf16_t* xb, float* sspart, int blk, int tid) {
;     ...
;         for (int nt = 0; nt < 4; ++nt) {
;             sum[nt] = part[(0 * 8 + ra * 4 + nt) * 64 + lane];
; #pragma unroll
;             for (int w = 1; w < 8; ++w) sum[nt] += part[(w * 8 + ra * 4 + nt) * 64 + lane];
;         }
;         float ss[4] = {0.f, 0.f, 0.f, 0.f};
; #pragma unroll
;         for (int j = 0; j < 4; ++j)
; #pragma unroll
;             for (int nt = 0; nt < 4; ++nt) {
;                 bf16_t* xp = xb + (size_t)(r0 + 16 * ra + 4 * g + j) * 2048 + 64 * cg + 16 * nt + l15;
;                 const bf16_t nv = f2bf(bf1(*xp) + sum[nt][j]);
;                 *xp = nv; const float r = bf1(nv); ss[j] += r * r;
;             }
; #pragma unroll
;         for (int j = 0; j < 4; ++j) {
;             float s = ss[j];
;             s += __shfl_xor(s, 1); s += __shfl_xor(s, 2); s += __shfl_xor(s, 4); s += __shfl_xor(s, 8);
;             if (l15 == 0) sspart[(size_t)(r0 + 16 * ra + 4 * g + j) * 32 + cg] = s;
;         }
	v_pk_add_f32 v[14:15], v[14:15], v[10:11]
	v_pk_add_f32 v[22:23], v[22:23], v[8:9]
	v_mov_b32_e32 v8, v196
	v_mov_b32_e32 v9, v197
	v_mov_b32_e32 v10, v198
	v_mov_b32_e32 v11, v199
	s_waitcnt lgkmcnt(0)
	v_pk_add_f32 v[14:15], v[14:15], v[10:11]
	v_pk_add_f32 v[22:23], v[22:23], v[8:9]
	v_mov_b32_e32 v8, v200
	v_mov_b32_e32 v9, v201
	v_mov_b32_e32 v10, v202
	v_mov_b32_e32 v11, v203
	s_waitcnt lgkmcnt(0)
	v_pk_add_f32 v[14:15], v[14:15], v[10:11]
	v_pk_add_f32 v[22:23], v[22:23], v[8:9]
	v_mov_b32_e32 v8, v204
	v_mov_b32_e32 v9, v205
	v_mov_b32_e32 v10, v206
	v_mov_b32_e32 v11, v207
	s_waitcnt lgkmcnt(0)
	v_pk_add_f32 v[10:11], v[14:15], v[10:11]
	v_pk_add_f32 v[14:15], v[22:23], v[8:9]
	v_pk_add_f32 v[8:9], v[10:11], v[36:37]
	v_add_u32_e32 v10, s21, v31
	v_ashrrev_i32_e32 v11, 31, v10
	v_pk_add_f32 v[22:23], v[14:15], v[34:35]
	v_lshlrev_b64 v[14:15], 12, v[10:11]
	v_lshl_add_u64 v[14:15], v[28:29], 0, v[14:15]
	s_waitcnt vmcnt(0)
	v_mov_b32_e32 v0, v146
	v_lshlrev_b32_e32 v0, 16, v0
	v_add_f32_e32 v0, v20, v0
	v_cvt_pk_bf16_f32 v0, v0, s0
	global_store_short v[14:15], v0, off
	v_lshlrev_b32_e32 v20, 16, v0
	v_mov_b32_e32 v0, v147
	v_lshlrev_b32_e32 v0, 16, v0
	v_add_f32_e32 v0, v26, v0
	v_cvt_pk_bf16_f32 v0, v0, s0
	global_store_short v[14:15], v0, off offset:32
	v_lshlrev_b32_e32 v0, 16, v0
	v_mul_f32_e32 v0, v0, v0
	v_fmac_f32_e32 v0, v20, v20
	v_mov_b32_e32 v20, v148
	v_lshlrev_b32_e32 v20, 16, v20
	v_add_f32_e32 v20, v24, v20
	v_cvt_pk_bf16_f32 v20, v20, s0
	global_store_short v[14:15], v20, off offset:64
	v_lshlrev_b32_e32 v20, 16, v20
	v_fmac_f32_e32 v0, v20, v20
	v_mov_b32_e32 v20, v149
	v_lshlrev_b32_e32 v20, 16, v20
	v_add_f32_e32 v20, v22, v20
	v_cvt_pk_bf16_f32 v20, v20, s0
	global_store_short v[14:15], v20, off offset:96
	v_lshlrev_b32_e32 v14, 16, v20
	v_fmac_f32_e32 v0, v14, v14
	v_or_b32_e32 v14, 1, v10
	v_ashrrev_i32_e32 v15, 31, v14
	v_lshlrev_b64 v[34:35], 12, v[14:15]
	v_lshl_add_u64 v[36:37], v[28:29], 0, v[34:35]
	v_mov_b32_e32 v20, v150
	v_lshlrev_b32_e32 v20, 16, v20
	v_add_f32_e32 v20, v21, v20
	v_cvt_pk_bf16_f32 v26, v20, s0
	v_mov_b32_e32 v20, v151
	v_lshlrev_b32_e32 v20, 16, v20
	v_add_f32_e32 v20, v27, v20
	v_cvt_pk_bf16_f32 v27, v20, s0
	v_mov_b32_e32 v20, v152
	v_lshlrev_b32_e32 v20, 16, v20
	v_add_f32_e32 v20, v25, v20
	v_cvt_pk_bf16_f32 v34, v20, s0
	v_mov_b32_e32 v20, v153
	v_lshlrev_b32_e32 v20, 16, v20
	v_add_f32_e32 v20, v23, v20
	v_cvt_pk_bf16_f32 v35, v20, s0
	v_or_b32_e32 v20, 2, v10
	v_ashrrev_i32_e32 v21, 31, v20
	v_lshlrev_b64 v[22:23], 12, v[20:21]
	v_lshl_add_u64 v[22:23], v[28:29], 0, v[22:23]
	v_mov_b32_e32 v24, v154
	v_lshlrev_b32_e32 v24, 16, v24
	v_add_f32_e32 v12, v12, v24
	v_mov_b32_e32 v24, v155
	v_cvt_pk_bf16_f32 v12, v12, s0
	global_store_short v[22:23], v12, off
	global_store_short v[36:37], v26, off
	global_store_short v[36:37], v27, off offset:32
	global_store_short v[36:37], v34, off offset:64
	global_store_short v[36:37], v35, off offset:96
	v_xor_b32_e32 v36, 8, v215
	s_waitcnt vmcnt(5)
	v_lshlrev_b32_e32 v24, 16, v24
	v_add_f32_e32 v18, v18, v24
	v_mov_b32_e32 v24, v156
	v_cvt_pk_bf16_f32 v18, v18, s0
	global_store_short v[22:23], v18, off offset:32
	s_waitcnt vmcnt(1)
	v_lshlrev_b32_e32 v24, 16, v24
	v_add_f32_e32 v16, v16, v24
	v_mov_b32_e32 v24, v157
	v_cvt_pk_bf16_f32 v16, v16, s0
	global_store_short v[22:23], v16, off offset:64
	s_waitcnt vmcnt(1)
	v_lshlrev_b32_e32 v24, 16, v24
	v_add_f32_e32 v8, v8, v24
	v_cvt_pk_bf16_f32 v8, v8, s0
	global_store_short v[22:23], v8, off offset:96
	v_or_b32_e32 v22, 3, v10
	v_ashrrev_i32_e32 v23, 31, v22
	v_lshlrev_b64 v[24:25], 12, v[22:23]
	v_lshl_add_u64 v[24:25], v[28:29], 0, v[24:25]
	v_mov_b32_e32 v28, v158
	v_lshlrev_b32_e32 v28, 16, v28
	v_add_f32_e32 v13, v13, v28
	v_mov_b32_e32 v28, v159
	v_cvt_pk_bf16_f32 v13, v13, s0
	global_store_short v[24:25], v13, off
	s_waitcnt vmcnt(1)
	v_lshlrev_b32_e32 v28, 16, v28
	v_add_f32_e32 v19, v19, v28
	v_mov_b32_e32 v28, v160
	v_cvt_pk_bf16_f32 v19, v19, s0
	global_store_short v[24:25], v19, off offset:32
	s_waitcnt vmcnt(1)
	v_lshlrev_b32_e32 v28, 16, v28
	v_add_f32_e32 v17, v17, v28
	v_mov_b32_e32 v28, v161
	v_cvt_pk_bf16_f32 v17, v17, s0
	global_store_short v[24:25], v17, off offset:64
	s_waitcnt vmcnt(1)
	v_lshlrev_b32_e32 v28, 16, v28
	v_add_f32_e32 v9, v9, v28
	v_cvt_pk_bf16_f32 v9, v9, s0
	global_store_short v[24:25], v9, off offset:96
	v_and_b32_e32 v25, 64, v215
	v_xor_b32_e32 v24, 1, v215
	v_add_u32_e32 v29, 64, v25
	v_cmp_lt_i32_e32 vcc, v24, v29
	v_xor_b32_e32 v25, 2, v215
	v_xor_b32_e32 v28, 4, v215
	v_cndmask_b32_e32 v24, v215, v24, vcc
	v_cmp_lt_i32_e32 vcc, v25, v29
	v_lshlrev_b32_e32 v24, 2, v24
	s_nop 0
	v_cndmask_b32_e32 v25, v215, v25, vcc
	v_cmp_lt_i32_e32 vcc, v28, v29
	v_lshlrev_b32_e32 v25, 2, v25
	s_nop 0
	v_cndmask_b32_e32 v28, v215, v28, vcc
	v_cmp_lt_i32_e32 vcc, v36, v29
	v_lshlrev_b32_e32 v28, 2, v28
	s_nop 0
	v_cndmask_b32_e32 v29, v215, v36, vcc
	ds_bpermute_b32 v36, v24, v0
	v_lshlrev_b32_e32 v29, 2, v29
	s_waitcnt lgkmcnt(0)
	v_add_f32_e32 v0, v0, v36
	ds_bpermute_b32 v36, v25, v0
	s_waitcnt lgkmcnt(0)
	v_add_f32_e32 v0, v0, v36
	ds_bpermute_b32 v36, v28, v0
	s_waitcnt lgkmcnt(0)
	v_add_f32_e32 v0, v0, v36
	ds_bpermute_b32 v36, v29, v0
	s_and_saveexec_b64 s[20:21], s[6:7]
	s_cbranch_execz .LBB0_1168
	v_lshlrev_b64 v[10:11], 7, v[10:11]
	v_lshl_add_u64 v[10:11], s[10:11], 0, v[10:11]
	s_waitcnt lgkmcnt(0)
	v_add_f32_e32 v0, v0, v36
	global_store_dword v[10:11], v0, off

; __device__ __forceinline__ float bf_lo(unsigned w) { return __uint_as_float(w << 16); }
; __device__ __forceinline__ float bf_hi(unsigned w) { return __uint_as_float(w & 0xffff0000u); }
; __device__ __forceinline__ unsigned pk2(float lo, float hi) { return pg8::cvt_pk_bf16(lo, hi); }
; __device__ __forceinline__ void xattn_prompt_item(const bf16_t* xq, const bf16_t* xq1, const bf16_t* memkv, const bf16_t* memvt, bf16_t* xo, int l, int it, int lane) {
;     ...
;     for (int ks = 0; ks < 4; ++ks) {
;         const u32x4 a = *(const u32x4*)(xq + tok * 512 + h * 128 + 32 * ks + 8 * g), c = *(const u32x4*)(xq1 + tok * 512 + h * 128 + 32 * ks + 8 * g);
;         u32x4 w; w.x = pk2(bf_lo(a.x) + bf_lo(c.x), bf_hi(a.x) + bf_hi(c.x)); w.y = pk2(bf_lo(a.y) + bf_lo(c.y), bf_hi(a.y) + bf_hi(c.y));
;         w.z = pk2(bf_lo(a.z) + bf_lo(c.z), bf_hi(a.z) + bf_hi(c.z)); w.w = pk2(bf_lo(a.w) + bf_lo(c.w), bf_hi(a.w) + bf_hi(c.w));
;         qf[ks] = as_bf16x8(w);
;     }
.Lxp_nostage:
	s_add_u32 s4, s14, s4
	s_addc_u32 s5, s15, 0
	s_waitcnt vmcnt(8)
	v_lshlrev_b32_e32 v8, 16, v96
	v_and_b32_e32 v9, 0xffff0000, v96
	v_lshlrev_b32_e32 v136, 16, v112
	v_and_b32_e32 v137, 0xffff0000, v112
	v_pk_add_f32 v[8:9], v[8:9], v[136:137]
	v_cvt_pk_bf16_f32 v10, v8, v9
	v_lshlrev_b32_e32 v8, 16, v97
	v_and_b32_e32 v9, 0xffff0000, v97
	v_lshlrev_b32_e32 v136, 16, v113
	v_and_b32_e32 v137, 0xffff0000, v113
	v_pk_add_f32 v[8:9], v[8:9], v[136:137]
	v_cvt_pk_bf16_f32 v11, v8, v9
	v_lshlrev_b32_e32 v8, 16, v98
	v_and_b32_e32 v9, 0xffff0000, v98
	v_lshlrev_b32_e32 v136, 16, v114
	v_and_b32_e32 v137, 0xffff0000, v114
	v_pk_add_f32 v[8:9], v[8:9], v[136:137]
	v_cvt_pk_bf16_f32 v12, v8, v9
	v_lshlrev_b32_e32 v8, 16, v99
	v_and_b32_e32 v9, 0xffff0000, v99
	v_lshlrev_b32_e32 v136, 16, v115
	v_and_b32_e32 v137, 0xffff0000, v115
	v_pk_add_f32 v[8:9], v[8:9], v[136:137]
	v_cvt_pk_bf16_f32 v13, v8, v9
	v_lshlrev_b32_e32 v8, 16, v100
	v_and_b32_e32 v9, 0xffff0000, v100
	v_lshlrev_b32_e32 v136, 16, v116
	v_and_b32_e32 v137, 0xffff0000, v116
	v_pk_add_f32 v[8:9], v[8:9], v[136:137]
	v_cvt_pk_bf16_f32 v14, v8, v9
	v_lshlrev_b32_e32 v8, 16, v101
	v_and_b32_e32 v9, 0xffff0000, v101
	v_lshlrev_b32_e32 v136, 16, v117
	v_and_b32_e32 v137, 0xffff0000, v117
	v_pk_add_f32 v[8:9], v[8:9], v[136:137]
	v_cvt_pk_bf16_f32 v15, v8, v9
	v_lshlrev_b32_e32 v8, 16, v102
	v_and_b32_e32 v9, 0xffff0000, v102
	v_lshlrev_b32_e32 v136, 16, v118
	v_and_b32_e32 v137, 0xffff0000, v118
	v_pk_add_f32 v[8:9], v[8:9], v[136:137]
	v_cvt_pk_bf16_f32 v16, v8, v9
	v_lshlrev_b32_e32 v8, 16, v103
	v_and_b32_e32 v9, 0xffff0000, v103
	v_lshlrev_b32_e32 v136, 16, v119
	v_and_b32_e32 v137, 0xffff0000, v119
	v_pk_add_f32 v[8:9], v[8:9], v[136:137]
	v_cvt_pk_bf16_f32 v17, v8, v9
	v_lshlrev_b32_e32 v8, 16, v104
	v_and_b32_e32 v9, 0xffff0000, v104
	v_lshlrev_b32_e32 v136, 16, v120
	v_and_b32_e32 v137, 0xffff0000, v120
	v_pk_add_f32 v[8:9], v[8:9], v[136:137]
	v_cvt_pk_bf16_f32 v18, v8, v9
	v_lshlrev_b32_e32 v8, 16, v105
	v_and_b32_e32 v9, 0xffff0000, v105
	v_lshlrev_b32_e32 v136, 16, v121
	v_and_b32_e32 v137, 0xffff0000, v121
	v_pk_add_f32 v[8:9], v[8:9], v[136:137]
	v_cvt_pk_bf16_f32 v19, v8, v9
	v_lshlrev_b32_e32 v8, 16, v106
	v_and_b32_e32 v9, 0xffff0000, v106
	v_lshlrev_b32_e32 v136, 16, v122
	v_and_b32_e32 v137, 0xffff0000, v122
	v_pk_add_f32 v[8:9], v[8:9], v[136:137]
	v_cvt_pk_bf16_f32 v20, v8, v9
	v_lshlrev_b32_e32 v8, 16, v107
	v_and_b32_e32 v9, 0xffff0000, v107
	v_lshlrev_b32_e32 v136, 16, v123
	v_and_b32_e32 v137, 0xffff0000, v123
	v_pk_add_f32 v[8:9], v[8:9], v[136:137]
	v_cvt_pk_bf16_f32 v21, v8, v9
	v_lshlrev_b32_e32 v8, 16, v108
	v_and_b32_e32 v9, 0xffff0000, v108
	v_lshlrev_b32_e32 v136, 16, v124
	v_and_b32_e32 v137, 0xffff0000, v124
	v_pk_add_f32 v[8:9], v[8:9], v[136:137]
	v_cvt_pk_bf16_f32 v22, v8, v9
	v_lshlrev_b32_e32 v8, 16, v109
	v_and_b32_e32 v9, 0xffff0000, v109
	v_lshlrev_b32_e32 v136, 16, v125
	v_and_b32_e32 v137, 0xffff0000, v125
	v_pk_add_f32 v[8:9], v[8:9], v[136:137]
	v_cvt_pk_bf16_f32 v23, v8, v9
	v_lshlrev_b32_e32 v8, 16, v110
	v_and_b32_e32 v9, 0xffff0000, v110
	v_lshlrev_b32_e32 v136, 16, v126
	v_and_b32_e32 v137, 0xffff0000, v126
	v_pk_add_f32 v[8:9], v[8:9], v[136:137]
	v_cvt_pk_bf16_f32 v24, v8, v9
	v_lshlrev_b32_e32 v8, 16, v111
	v_and_b32_e32 v9, 0xffff0000, v111
	v_lshlrev_b32_e32 v136, 16, v127
	v_and_b32_e32 v137, 0xffff0000, v127
	v_pk_add_f32 v[8:9], v[8:9], v[136:137]
	v_cvt_pk_bf16_f32 v25, v8, v9

; #define LAS __attribute__((address_space(3)))
; __device__ __forceinline__ void sample_out_block(LAS unsigned char* lds, const bf16_t* A, const bf16_t* Bt, int K, bf16_t* xb, float* sspart, int blk, int tid) {
;     const int wave = tid >> 6, lane = tid & 63, l15 = lane & 15, g = lane >> 4;
;     const int rt = blk >> 5, cg = blk & 31, r0 = T_P + 32 * rt;
;     const int kq = K >> 3;
;     f32x4 acc[2][4];
; #pragma unroll
;     for (int ra = 0; ra < 2; ++ra)
; #pragma unroll
;         for (int nt = 0; nt < 4; ++nt) acc[ra][nt] = (f32x4){0.f, 0.f, 0.f, 0.f};
;     {
;         const bf16_t* ap = A + (size_t)(r0 + l15) * K + wave * kq + 8 * g;
;         const bf16_t* bp = Bt + (size_t)(64 * cg + l15) * K + wave * kq + 8 * g;
;         bf16x8 af[2][2], bf[2][4], afn[2][2], bfn[2][4];
; #pragma unroll
;         for (int s = 0; s < 2; ++s) {
; #pragma unroll
;             for (int ra = 0; ra < 2; ++ra) af[s][ra] = *(const bf16x8*)(ap + (size_t)(16 * ra) * K + 32 * s);
; #pragma unroll
;             for (int nt = 0; nt < 4; ++nt) bf[s][nt] = *(const bf16x8*)(bp + (size_t)(16 * nt) * K + 32 * s);
;         }
;         for (int k0 = 0; k0 < kq; k0 += 64) {
;             const int k1 = (k0 + 64 < kq) ? k0 + 64 : k0;
; #pragma unroll
;             for (int s = 0; s < 2; ++s) {
; #pragma unroll
;                 for (int ra = 0; ra < 2; ++ra) afn[s][ra] = *(const bf16x8*)(ap + (size_t)(16 * ra) * K + k1 + 32 * s);
; #pragma unroll
;                 for (int nt = 0; nt < 4; ++nt) bfn[s][nt] = *(const bf16x8*)(bp + (size_t)(16 * nt) * K + k1 + 32 * s);
;             }
; #pragma unroll
;             for (int s = 0; s < 2; ++s)
; #pragma unroll
;                 for (int ra = 0; ra < 2; ++ra)
; #pragma unroll
;                     for (int nt = 0; nt < 4; ++nt) acc[ra][nt] = MFMA16(af[s][ra], bf[s][nt], acc[ra][nt]);
; #pragma unroll
;             for (int s = 0; s < 2; ++s) {
; #pragma unroll
;                 for (int ra = 0; ra < 2; ++ra) af[s][ra] = afn[s][ra];
; #pragma unroll
;                 for (int nt = 0; nt < 4; ++nt) bf[s][nt] = bfn[s][nt];
;             }
;         }
;     }
;     LAS f32x4* part = (LAS f32x4*)lds;
; #pragma unroll
;     for (int ra = 0; ra < 2; ++ra)
; #pragma unroll
;         for (int nt = 0; nt < 4; ++nt) part[(wave * 8 + ra * 4 + nt) * 64 + lane] = acc[ra][nt];
;     __syncthreads();
.LBB0_1463:
	s_and_b32 s19, s26, 0xffffffe0
	s_addk_i32 s19, 0x2000
	s_and_b32 s18, s26, 31
	v_or_b32_e32 v8, s19, v30
	v_ashrrev_i32_e32 v9, 31, v8
	s_lshl_b32 s20, s18, 6
	v_lshlrev_b64 v[8:9], 10, v[8:9]
	v_or_b32_e32 v0, s20, v30
	v_lshl_add_u64 v[28:29], v[2:3], 0, v[8:9]
	v_lshlrev_b32_e32 v0, 10, v0
	v_lshl_add_u64 v[42:43], v[4:5], 0, v[0:1]
	v_add_co_u32_e32 v66, vcc, 0x4000, v28
	s_mov_b64 s[8:9], vcc
	v_add_co_u32_e32 v24, vcc, 0x4000, v42
	v_readfirstlane_b32 s36, v139
	s_lshr_b32 s36, s36, 6
	s_and_b32 s37, s26, 0xffffffe0
	s_addk_i32 s37, 0x2000
	s_and_b32 s38, s26, 31
	s_lshl_b32 s38, s38, 6
	s_lshl_b32 s39, s37, 10
	s_mul_i32 s40, s36, 0x80
	s_add_u32 s42, s16, s39
	s_addc_u32 s43, s17, 0
	s_add_u32 s42, s42, s40
	s_addc_u32 s43, s43, 0
	s_lshl_b32 s41, s24, 1
	s_lshl_b32 s39, s38, 10
	s_add_u32 s44, s22, s41
	s_addc_u32 s45, s23, 0
	s_add_u32 s44, s44, s39
	s_addc_u32 s45, s45, 0
	s_add_u32 s44, s44, s40
	s_addc_u32 s45, s45, 0
	v_lshrrev_b32_e32 v227, 3, v215
	v_and_b32_e32 v228, 7, v215
	v_lshlrev_b32_e32 v198, 10, v227
	v_lshl_add_u32 v198, v228, 4, v198
	v_add_u32_e32 v199, 0x2000, v198
	v_add_u32_e32 v200, 0x4000, v198
	v_add_u32_e32 v201, 0x6000, v198
	v_add_u32_e32 v202, 0x8000, v198
	v_add_u32_e32 v203, 0xa000, v198
	v_add_u32_e32 v204, 0xc000, v198
	v_add_u32_e32 v205, 0xe000, v198
	s_lshl_b32 s46, s36, 13
	s_mul_i32 s47, s36, 0x1800
	s_add_i32 s47, s47, 0x10000
	v_mul_u32_u24_e32 v206, 0x90, v227
	v_lshl_add_u32 v206, v228, 4, v206
	v_add_u32_e32 v207, s47, v206
	v_add_u32_e32 v206, s46, v206
	v_and_b32_e32 v227, 15, v215
	v_lshrrev_b32_e32 v228, 4, v215
	v_mul_u32_u24_e32 v208, 0x90, v227
	v_lshl_add_u32 v208, v228, 4, v208
	v_add_u32_e32 v209, s47, v208
	v_add_u32_e32 v208, s46, v208
	v_add_u32_e32 v226, 0x1b00, v208
	v_subrev_u32_e32 v228, 0x480, v209
	v_cmp_gt_u32_e32 vcc, 8, v227
	v_cndmask_b32_e32 v226, v228, v226, vcc
	global_load_dwordx4 v[34:37], v198, s[42:43]
	global_load_dwordx4 v[38:41], v199, s[42:43]
	global_load_dwordx4 v[42:45], v200, s[42:43]
	global_load_dwordx4 v[46:49], v201, s[42:43]
	global_load_dwordx4 v[50:53], v198, s[44:45]
	global_load_dwordx4 v[54:57], v199, s[44:45]
	global_load_dwordx4 v[58:61], v200, s[44:45]
	global_load_dwordx4 v[62:65], v201, s[44:45]
	global_load_dwordx4 v[66:69], v202, s[44:45]
	global_load_dwordx4 v[70:73], v203, s[44:45]
	global_load_dwordx4 v[74:77], v204, s[44:45]
	global_load_dwordx4 v[78:81], v205, s[44:45]
	s_waitcnt vmcnt(11)
	ds_write_b128 v206, v[34:37]
	s_waitcnt vmcnt(10)
	ds_write_b128 v206, v[38:41] offset:1152
	s_waitcnt vmcnt(9)
	ds_write_b128 v206, v[42:45] offset:2304
	s_waitcnt vmcnt(8)
	ds_write_b128 v206, v[46:49] offset:3456
	s_waitcnt vmcnt(7)
	ds_write_b128 v206, v[50:53] offset:4608
	s_waitcnt vmcnt(6)
	ds_write_b128 v206, v[54:57] offset:5760
	s_waitcnt vmcnt(5)
	ds_write_b128 v206, v[58:61] offset:6912
	s_waitcnt vmcnt(4)
	ds_write_b128 v207, v[62:65]
	s_waitcnt vmcnt(3)
	ds_write_b128 v207, v[66:69] offset:1152
	s_waitcnt vmcnt(2)
	ds_write_b128 v207, v[70:73] offset:2304
	s_waitcnt vmcnt(1)
	ds_write_b128 v207, v[74:77] offset:3456
	s_waitcnt vmcnt(0)
	ds_write_b128 v207, v[78:81] offset:4608
	ds_read_b128 v[146:149], v208 offset:0
	ds_read_b128 v[150:153], v208 offset:2304
	ds_read_b128 v[154:157], v208 offset:4608
	ds_read_b128 v[158:161], v226
	ds_read_b128 v[162:165], v209 offset:1152
	ds_read_b128 v[166:169], v209 offset:3456
	ds_read_b128 v[170:173], v208 offset:64
	ds_read_b128 v[174:177], v208 offset:2368
	ds_read_b128 v[178:181], v208 offset:4672
	ds_read_b128 v[182:185], v226 offset:64
	ds_read_b128 v[186:189], v209 offset:1216
	ds_read_b128 v[190:193], v209 offset:3520
	s_waitcnt lgkmcnt(6)
	v_mfma_f32_16x16x32_bf16 v[8:11], v[146:149], v[154:157], 0
	v_mfma_f32_16x16x32_bf16 v[12:15], v[146:149], v[158:161], 0
	v_mfma_f32_16x16x32_bf16 v[16:19], v[146:149], v[162:165], 0
	v_mfma_f32_16x16x32_bf16 v[20:23], v[146:149], v[166:169], 0
	v_mfma_f32_16x16x32_bf16 v[24:27], v[150:153], v[154:157], 0
	v_mfma_f32_16x16x32_bf16 v[130:133], v[150:153], v[158:161], 0
	v_mfma_f32_16x16x32_bf16 v[134:137], v[150:153], v[162:165], 0
	v_mfma_f32_16x16x32_bf16 v[194:197], v[150:153], v[166:169], 0
	s_waitcnt lgkmcnt(0)
	v_mfma_f32_16x16x32_bf16 v[8:11], v[170:173], v[178:181], v[8:11]
	v_mfma_f32_16x16x32_bf16 v[12:15], v[170:173], v[182:185], v[12:15]
	v_mfma_f32_16x16x32_bf16 v[16:19], v[170:173], v[186:189], v[16:19]
	v_mfma_f32_16x16x32_bf16 v[20:23], v[170:173], v[190:193], v[20:23]
	v_mfma_f32_16x16x32_bf16 v[24:27], v[174:177], v[178:181], v[24:27]
	v_mfma_f32_16x16x32_bf16 v[130:133], v[174:177], v[182:185], v[130:133]
	v_mfma_f32_16x16x32_bf16 v[134:137], v[174:177], v[186:189], v[134:137]
	v_mfma_f32_16x16x32_bf16 v[194:197], v[174:177], v[190:193], v[194:197]
	s_nop 7
	s_nop 7
	ds_write_b128 v32, v[8:11]
	ds_write_b128 v32, v[12:15] offset:1024
	ds_write_b128 v32, v[16:19] offset:2048
	ds_write_b128 v32, v[20:23] offset:3072
	ds_write_b128 v32, v[24:27] offset:4096
	ds_write_b128 v32, v[130:133] offset:5120
	ds_write_b128 v32, v[134:137] offset:6144
	ds_write_b128 v32, v[194:197] offset:7168
	s_waitcnt lgkmcnt(0)
	s_barrier
	s_and_saveexec_b64 s[8:9], s[4:5]
	s_cbranch_execz .LBB0_1462
; __device__ __forceinline__ float bf1(bf16_t h) { return __uint_as_float((unsigned)h << 16); }
; __device__ __forceinline__ bf16_t f2bf(float f) { return (bf16_t)(pk2(f, 0.f) & 0xffffu); }
; __device__ __forceinline__ void sample_out_block(LAS unsigned char* lds, const bf16_t* A, const bf16_t* Bt, int K, bf16_t* xb, float* sspart, int blk, int tid) {
;     ...
;     if (wave < 2) {
;         const int ra = wave;
;         f32x4 sum[4];
; #pragma unroll
;         for (int nt = 0; nt < 4; ++nt) {
;             sum[nt] = part[(0 * 8 + ra * 4 + nt) * 64 + lane];
; #pragma unroll
;             for (int w = 1; w < 8; ++w) sum[nt] += part[(w * 8 + ra * 4 + nt) * 64 + lane];
;         }
;         float ss[4] = {0.f, 0.f, 0.f, 0.f};
; #pragma unroll
;         for (int j = 0; j < 4; ++j)
; #pragma unroll
;             for (int nt = 0; nt < 4; ++nt) {
;                 bf16_t* xp = xb + (size_t)(r0 + 16 * ra + 4 * g + j) * 2048 + 64 * cg + 16 * nt + l15;
;                 const bf16_t nv = f2bf(bf1(*xp) + sum[nt][j]);
	v_add_u32_e32 v170, s19, v31
	v_lshlrev_b32_e32 v170, 12, v170
	s_lshl_b32 s36, s20, 1
	v_add_u32_e32 v170, s36, v170
	v_mov_b32_e32 v171, 0
	s_mov_b64 s[38:39], 0x1000
	v_lshl_add_u64 v[162:163], v[6:7], 0, v[170:171]
	v_lshl_add_u64 v[164:165], v[162:163], 0, s[38:39]
	v_lshl_add_u64 v[166:167], v[164:165], 0, s[38:39]
	v_lshl_add_u64 v[168:169], v[166:167], 0, s[38:39]
	global_load_ushort v146, v[162:163], off
	global_load_ushort v147, v[162:163], off offset:32
	global_load_ushort v148, v[162:163], off offset:64
	global_load_ushort v149, v[162:163], off offset:96
	global_load_ushort v150, v[164:165], off
	global_load_ushort v151, v[164:165], off offset:32
	global_load_ushort v152, v[164:165], off offset:64
	global_load_ushort v153, v[164:165], off offset:96
	global_load_ushort v154, v[166:167], off
	global_load_ushort v155, v[166:167], off offset:32
	global_load_ushort v156, v[166:167], off offset:64
	global_load_ushort v157, v[166:167], off offset:96
	global_load_ushort v158, v[168:169], off
	global_load_ushort v159, v[168:169], off offset:32
	global_load_ushort v160, v[168:169], off offset:64
	global_load_ushort v161, v[168:169], off offset:96
	ds_read_b128 v[38:41], v33
	ds_read_b128 v[42:45], v33 offset:8192
	ds_read_b128 v[46:49], v33 offset:16384
	ds_read_b128 v[50:53], v33 offset:24576
	ds_read_b128 v[54:57], v33 offset:32768
	ds_read_b128 v[58:61], v33 offset:40960
	ds_read_b128 v[62:65], v33 offset:49152
	ds_read_b128 v[66:69], v33 offset:57344
	ds_read_b128 v[70:73], v33 offset:1024
	ds_read_b128 v[74:77], v33 offset:9216
	ds_read_b128 v[78:81], v33 offset:17408
	ds_read_b128 v[82:85], v33 offset:25600
	ds_read_b128 v[86:89], v33 offset:33792
	ds_read_b128 v[90:93], v33 offset:41984
	ds_read_b128 v[94:97], v33 offset:50176
	ds_read_b128 v[98:101], v33 offset:58368
	ds_read_b128 v[102:105], v33 offset:2048
	ds_read_b128 v[106:109], v33 offset:10240
	ds_read_b128 v[110:113], v33 offset:18432
	ds_read_b128 v[114:117], v33 offset:26624
	ds_read_b128 v[118:121], v33 offset:34816
	ds_read_b128 v[122:125], v33 offset:43008
	ds_read_b128 v[126:129], v33 offset:51200
	ds_read_b128 v[172:175], v33 offset:59392
	ds_read_b128 v[176:179], v33 offset:3072
	ds_read_b128 v[180:183], v33 offset:11264
	ds_read_b128 v[184:187], v33 offset:19456
	ds_read_b128 v[188:191], v33 offset:60416
	ds_read_b128 v[192:195], v33 offset:27648
	ds_read_b128 v[196:199], v33 offset:35840
	ds_read_b128 v[200:203], v33 offset:44032
	ds_read_b128 v[204:207], v33 offset:52224
	s_waitcnt lgkmcnt(0)
	v_mov_b32_e32 v8, v38
	v_mov_b32_e32 v9, v39
	v_mov_b32_e32 v10, v40
	v_mov_b32_e32 v11, v41
	v_mov_b32_e32 v12, v42
	v_mov_b32_e32 v13, v43
	v_mov_b32_e32 v14, v44
	v_mov_b32_e32 v15, v45
	s_lshl_b32 s80, s20, 1
	v_lshl_add_u64 v[28:29], v[6:7], 0, s[80:81]
	s_lshl_b32 s18, s18, 2
	s_add_u32 s18, s14, s18
	s_waitcnt lgkmcnt(0)
	v_pk_add_f32 v[14:15], v[10:11], v[14:15]
	v_pk_add_f32 v[12:13], v[8:9], v[12:13]
	v_mov_b32_e32 v8, v46
	v_mov_b32_e32 v9, v47
	v_mov_b32_e32 v10, v48
	v_mov_b32_e32 v11, v49
	s_waitcnt lgkmcnt(0)
	v_pk_add_f32 v[14:15], v[14:15], v[10:11]
	v_pk_add_f32 v[12:13], v[12:13], v[8:9]
	v_mov_b32_e32 v8, v50
	v_mov_b32_e32 v9, v51
	v_mov_b32_e32 v10, v52
	v_mov_b32_e32 v11, v53
	s_waitcnt lgkmcnt(0)
	v_pk_add_f32 v[14:15], v[14:15], v[10:11]
	v_pk_add_f32 v[12:13], v[12:13], v[8:9]
	v_mov_b32_e32 v8, v54
	v_mov_b32_e32 v9, v55
	v_mov_b32_e32 v10, v56
	v_mov_b32_e32 v11, v57
	s_waitcnt lgkmcnt(0)
	v_pk_add_f32 v[14:15], v[14:15], v[10:11]
	v_pk_add_f32 v[12:13], v[12:13], v[8:9]
	v_mov_b32_e32 v8, v58
	v_mov_b32_e32 v9, v59
	v_mov_b32_e32 v10, v60
	v_mov_b32_e32 v11, v61
	s_waitcnt lgkmcnt(0)
	v_pk_add_f32 v[14:15], v[14:15], v[10:11]
	v_pk_add_f32 v[12:13], v[12:13], v[8:9]
	v_mov_b32_e32 v8, v62
	v_mov_b32_e32 v9, v63
	v_mov_b32_e32 v10, v64
	v_mov_b32_e32 v11, v65
	s_waitcnt lgkmcnt(0)
	v_pk_add_f32 v[14:15], v[14:15], v[10:11]
	v_pk_add_f32 v[16:17], v[12:13], v[8:9]
	v_mov_b32_e32 v8, v66
	v_mov_b32_e32 v9, v67
	v_mov_b32_e32 v10, v68
	v_mov_b32_e32 v11, v69
	s_waitcnt lgkmcnt(0)
	v_pk_add_f32 v[12:13], v[14:15], v[10:11]
	v_pk_add_f32 v[20:21], v[16:17], v[8:9]
	v_mov_b32_e32 v8, v70
	v_mov_b32_e32 v9, v71
	v_mov_b32_e32 v10, v72
	v_mov_b32_e32 v11, v73
	v_mov_b32_e32 v14, v74
	v_mov_b32_e32 v15, v75
	v_mov_b32_e32 v16, v76
	v_mov_b32_e32 v17, v77
	s_waitcnt lgkmcnt(0)
	v_pk_add_f32 v[16:17], v[10:11], v[16:17]
	v_pk_add_f32 v[14:15], v[8:9], v[14:15]
	v_mov_b32_e32 v8, v78
	v_mov_b32_e32 v9, v79
	v_mov_b32_e32 v10, v80
	v_mov_b32_e32 v11, v81
	s_waitcnt lgkmcnt(0)
	v_pk_add_f32 v[16:17], v[16:17], v[10:11]
	v_pk_add_f32 v[14:15], v[14:15], v[8:9]
	v_mov_b32_e32 v8, v82
	v_mov_b32_e32 v9, v83
	v_mov_b32_e32 v10, v84
	v_mov_b32_e32 v11, v85
	s_waitcnt lgkmcnt(0)
	v_pk_add_f32 v[16:17], v[16:17], v[10:11]
	v_pk_add_f32 v[14:15], v[14:15], v[8:9]
	v_mov_b32_e32 v8, v86
	v_mov_b32_e32 v9, v87
	v_mov_b32_e32 v10, v88
	v_mov_b32_e32 v11, v89
	s_waitcnt lgkmcnt(0)
	v_pk_add_f32 v[16:17], v[16:17], v[10:11]
	v_pk_add_f32 v[14:15], v[14:15], v[8:9]
	v_mov_b32_e32 v8, v90
	v_mov_b32_e32 v9, v91
	v_mov_b32_e32 v10, v92
	v_mov_b32_e32 v11, v93
	s_waitcnt lgkmcnt(0)
	v_pk_add_f32 v[16:17], v[16:17], v[10:11]
	v_pk_add_f32 v[14:15], v[14:15], v[8:9]
	v_mov_b32_e32 v8, v94
	v_mov_b32_e32 v9, v95
	v_mov_b32_e32 v10, v96
	v_mov_b32_e32 v11, v97
	s_waitcnt lgkmcnt(0)
	v_pk_add_f32 v[16:17], v[16:17], v[10:11]
	v_pk_add_f32 v[14:15], v[14:15], v[8:9]
	v_mov_b32_e32 v8, v98
	v_mov_b32_e32 v9, v99
	v_mov_b32_e32 v10, v100
	v_mov_b32_e32 v11, v101
	s_waitcnt lgkmcnt(0)
; __device__ __forceinline__ float bf1(bf16_t h) { return __uint_as_float((unsigned)h << 16); }
; __device__ __forceinline__ bf16_t f2bf(float f) { return (bf16_t)(pk2(f, 0.f) & 0xffffu); }
; __device__ __forceinline__ void sample_out_block(LAS unsigned char* lds, const bf16_t* A, const bf16_t* Bt, int K, bf16_t* xb, float* sspart, int blk, int tid) {
;     ...
;         for (int nt = 0; nt < 4; ++nt) {
;             sum[nt] = part[(0 * 8 + ra * 4 + nt) * 64 + lane];
; #pragma unroll
;             for (int w = 1; w < 8; ++w) sum[nt] += part[(w * 8 + ra * 4 + nt) * 64 + lane];
;         }
;         float ss[4] = {0.f, 0.f, 0.f, 0.f};
; #pragma unroll
;         for (int j = 0; j < 4; ++j)
; #pragma unroll
;             for (int nt = 0; nt < 4; ++nt) {
;                 bf16_t* xp = xb + (size_t)(r0 + 16 * ra + 4 * g + j) * 2048 + 64 * cg + 16 * nt + l15;
;                 const bf16_t nv = f2bf(bf1(*xp) + sum[nt][j]);
;                 *xp = nv; const float r = bf1(nv); ss[j] += r * r;
	v_pk_add_f32 v[18:19], v[16:17], v[10:11]
	v_pk_add_f32 v[26:27], v[14:15], v[8:9]
	v_mov_b32_e32 v8, v102
	v_mov_b32_e32 v9, v103
	v_mov_b32_e32 v10, v104
	v_mov_b32_e32 v11, v105
	v_mov_b32_e32 v14, v106
	v_mov_b32_e32 v15, v107
	v_mov_b32_e32 v16, v108
	v_mov_b32_e32 v17, v109
	s_waitcnt lgkmcnt(0)
	v_pk_add_f32 v[16:17], v[10:11], v[16:17]
	v_pk_add_f32 v[14:15], v[8:9], v[14:15]
	v_mov_b32_e32 v8, v110
	v_mov_b32_e32 v9, v111
	v_mov_b32_e32 v10, v112
	v_mov_b32_e32 v11, v113
	s_waitcnt lgkmcnt(0)
	v_pk_add_f32 v[16:17], v[16:17], v[10:11]
	v_pk_add_f32 v[14:15], v[14:15], v[8:9]
	v_mov_b32_e32 v8, v114
	v_mov_b32_e32 v9, v115
	v_mov_b32_e32 v10, v116
	v_mov_b32_e32 v11, v117
	s_waitcnt lgkmcnt(0)
	v_pk_add_f32 v[16:17], v[16:17], v[10:11]
	v_pk_add_f32 v[14:15], v[14:15], v[8:9]
	v_mov_b32_e32 v8, v118
	v_mov_b32_e32 v9, v119
	v_mov_b32_e32 v10, v120
	v_mov_b32_e32 v11, v121
	s_waitcnt lgkmcnt(0)
	v_pk_add_f32 v[16:17], v[16:17], v[10:11]
	v_pk_add_f32 v[14:15], v[14:15], v[8:9]
	v_mov_b32_e32 v8, v122
	v_mov_b32_e32 v9, v123
	v_mov_b32_e32 v10, v124
	v_mov_b32_e32 v11, v125
	s_waitcnt lgkmcnt(0)
	v_pk_add_f32 v[16:17], v[16:17], v[10:11]
	v_pk_add_f32 v[14:15], v[14:15], v[8:9]
	v_mov_b32_e32 v8, v126
	v_mov_b32_e32 v9, v127
	v_mov_b32_e32 v10, v128
	v_mov_b32_e32 v11, v129
	s_waitcnt lgkmcnt(0)
	v_pk_add_f32 v[16:17], v[16:17], v[10:11]
	v_pk_add_f32 v[14:15], v[14:15], v[8:9]
	v_mov_b32_e32 v8, v172
	v_mov_b32_e32 v9, v173
	v_mov_b32_e32 v10, v174
	v_mov_b32_e32 v11, v175
	s_waitcnt lgkmcnt(0)
	v_pk_add_f32 v[16:17], v[16:17], v[10:11]
	v_pk_add_f32 v[24:25], v[14:15], v[8:9]
	v_mov_b32_e32 v8, v176
	v_mov_b32_e32 v9, v177
	v_mov_b32_e32 v10, v178
	v_mov_b32_e32 v11, v179
	v_mov_b32_e32 v34, v180
	v_mov_b32_e32 v35, v181
	v_mov_b32_e32 v36, v182
	v_mov_b32_e32 v37, v183
	s_waitcnt lgkmcnt(0)
	v_pk_add_f32 v[14:15], v[10:11], v[36:37]
	v_pk_add_f32 v[22:23], v[8:9], v[34:35]
	v_mov_b32_e32 v8, v184
	v_mov_b32_e32 v9, v185
	v_mov_b32_e32 v10, v186
	v_mov_b32_e32 v11, v187
	v_mov_b32_e32 v34, v188
	v_mov_b32_e32 v35, v189
	v_mov_b32_e32 v36, v190
	v_mov_b32_e32 v37, v191
	s_waitcnt lgkmcnt(1)
	v_pk_add_f32 v[14:15], v[14:15], v[10:11]
	v_pk_add_f32 v[22:23], v[22:23], v[8:9]
	v_mov_b32_e32 v8, v192
	v_mov_b32_e32 v9, v193
	v_mov_b32_e32 v10, v194
	v_mov_b32_e32 v11, v195
	s_waitcnt lgkmcnt(0)
	v_pk_add_f32 v[14:15], v[14:15], v[10:11]
	v_pk_add_f32 v[22:23], v[22:23], v[8:9]
	v_mov_b32_e32 v8, v196
	v_mov_b32_e32 v9, v197
	v_mov_b32_e32 v10, v198
	v_mov_b32_e32 v11, v199
	s_waitcnt lgkmcnt(0)
	v_pk_add_f32 v[14:15], v[14:15], v[10:11]
	v_pk_add_f32 v[22:23], v[22:23], v[8:9]
	v_mov_b32_e32 v8, v200
	v_mov_b32_e32 v9, v201
	v_mov_b32_e32 v10, v202
	v_mov_b32_e32 v11, v203
	s_waitcnt lgkmcnt(0)
	v_pk_add_f32 v[14:15], v[14:15], v[10:11]
	v_pk_add_f32 v[22:23], v[22:23], v[8:9]
	v_mov_b32_e32 v8, v204
	v_mov_b32_e32 v9, v205
	v_mov_b32_e32 v10, v206
	v_mov_b32_e32 v11, v207
	s_waitcnt lgkmcnt(0)
	v_pk_add_f32 v[10:11], v[14:15], v[10:11]
	v_pk_add_f32 v[14:15], v[22:23], v[8:9]
	v_pk_add_f32 v[8:9], v[10:11], v[36:37]
	v_add_u32_e32 v10, s19, v31
	v_ashrrev_i32_e32 v11, 31, v10
	v_pk_add_f32 v[22:23], v[14:15], v[34:35]
	v_lshlrev_b64 v[14:15], 12, v[10:11]
	v_lshl_add_u64 v[14:15], v[28:29], 0, v[14:15]
	s_waitcnt vmcnt(0)
	v_mov_b32_e32 v0, v146
	s_addc_u32 s19, s15, 0
	s_waitcnt vmcnt(0)
; __device__ __forceinline__ float bf1(bf16_t h) { return __uint_as_float((unsigned)h << 16); }
; __device__ __forceinline__ bf16_t f2bf(float f) { return (bf16_t)(pk2(f, 0.f) & 0xffffu); }
; __device__ __forceinline__ void sample_out_block(LAS unsigned char* lds, const bf16_t* A, const bf16_t* Bt, int K, bf16_t* xb, float* sspart, int blk, int tid) {
;     ...
;         float ss[4] = {0.f, 0.f, 0.f, 0.f};
; #pragma unroll
;         for (int j = 0; j < 4; ++j)
; #pragma unroll
;             for (int nt = 0; nt < 4; ++nt) {
;                 bf16_t* xp = xb + (size_t)(r0 + 16 * ra + 4 * g + j) * 2048 + 64 * cg + 16 * nt + l15;
;                 const bf16_t nv = f2bf(bf1(*xp) + sum[nt][j]);
;                 *xp = nv; const float r = bf1(nv); ss[j] += r * r;
;             }
; #pragma unroll
;         for (int j = 0; j < 4; ++j) {
;             float s = ss[j];
;             s += __shfl_xor(s, 1); s += __shfl_xor(s, 2); s += __shfl_xor(s, 4); s += __shfl_xor(s, 8);
;             if (l15 == 0) sspart[(size_t)(r0 + 16 * ra + 4 * g + j) * 32 + cg] = s;
;         }
	v_lshlrev_b32_e32 v0, 16, v0
	v_add_f32_e32 v0, v20, v0
	v_cvt_pk_bf16_f32 v0, v0, s0
	global_store_short v[14:15], v0, off
	v_lshlrev_b32_e32 v20, 16, v0
	v_mov_b32_e32 v0, v147
	v_lshlrev_b32_e32 v0, 16, v0
	v_add_f32_e32 v0, v26, v0
	v_cvt_pk_bf16_f32 v0, v0, s0
	global_store_short v[14:15], v0, off offset:32
	v_lshlrev_b32_e32 v0, 16, v0
	v_mul_f32_e32 v0, v0, v0
	v_fmac_f32_e32 v0, v20, v20
	v_mov_b32_e32 v20, v148
	v_lshlrev_b32_e32 v20, 16, v20
	v_add_f32_e32 v20, v24, v20
	v_cvt_pk_bf16_f32 v20, v20, s0
	global_store_short v[14:15], v20, off offset:64
	v_lshlrev_b32_e32 v20, 16, v20
	v_fmac_f32_e32 v0, v20, v20
	v_mov_b32_e32 v20, v149
	v_lshlrev_b32_e32 v20, 16, v20
	v_add_f32_e32 v20, v22, v20
	v_cvt_pk_bf16_f32 v20, v20, s0
	global_store_short v[14:15], v20, off offset:96
	v_lshlrev_b32_e32 v14, 16, v20
	v_fmac_f32_e32 v0, v14, v14
	v_or_b32_e32 v14, 1, v10
	v_ashrrev_i32_e32 v15, 31, v14
	v_lshlrev_b64 v[34:35], 12, v[14:15]
	v_lshl_add_u64 v[36:37], v[28:29], 0, v[34:35]
	v_mov_b32_e32 v20, v150
	v_lshlrev_b32_e32 v20, 16, v20
	v_add_f32_e32 v20, v21, v20
	v_cvt_pk_bf16_f32 v26, v20, s0
	v_mov_b32_e32 v20, v151
	v_lshlrev_b32_e32 v20, 16, v20
	v_add_f32_e32 v20, v27, v20
	v_cvt_pk_bf16_f32 v27, v20, s0
	v_mov_b32_e32 v20, v152
	v_lshlrev_b32_e32 v20, 16, v20
	v_add_f32_e32 v20, v25, v20
	v_cvt_pk_bf16_f32 v34, v20, s0
	v_mov_b32_e32 v20, v153
	v_lshlrev_b32_e32 v20, 16, v20
	v_add_f32_e32 v20, v23, v20
	v_cvt_pk_bf16_f32 v35, v20, s0
	v_or_b32_e32 v20, 2, v10
	v_ashrrev_i32_e32 v21, 31, v20
	v_lshlrev_b64 v[22:23], 12, v[20:21]
	v_lshl_add_u64 v[22:23], v[28:29], 0, v[22:23]
	v_mov_b32_e32 v24, v154
	v_lshlrev_b32_e32 v24, 16, v24
	v_add_f32_e32 v12, v12, v24
	v_mov_b32_e32 v24, v155
	v_cvt_pk_bf16_f32 v12, v12, s0
	global_store_short v[22:23], v12, off
	global_store_short v[36:37], v26, off
	global_store_short v[36:37], v27, off offset:32
	global_store_short v[36:37], v34, off offset:64
	global_store_short v[36:37], v35, off offset:96
	v_xor_b32_e32 v36, 8, v215
	s_waitcnt vmcnt(5)
	v_lshlrev_b32_e32 v24, 16, v24
	v_add_f32_e32 v18, v18, v24
	v_mov_b32_e32 v24, v156
	v_cvt_pk_bf16_f32 v18, v18, s0
	global_store_short v[22:23], v18, off offset:32
	s_waitcnt vmcnt(1)
	v_lshlrev_b32_e32 v24, 16, v24
	v_add_f32_e32 v16, v16, v24
	v_mov_b32_e32 v24, v157
	v_cvt_pk_bf16_f32 v16, v16, s0
	global_store_short v[22:23], v16, off offset:64
	s_waitcnt vmcnt(1)
	v_lshlrev_b32_e32 v24, 16, v24
	v_add_f32_e32 v8, v8, v24
	v_cvt_pk_bf16_f32 v8, v8, s0
	global_store_short v[22:23], v8, off offset:96
	v_or_b32_e32 v22, 3, v10
	v_ashrrev_i32_e32 v23, 31, v22
	v_lshlrev_b64 v[24:25], 12, v[22:23]
	v_lshl_add_u64 v[24:25], v[28:29], 0, v[24:25]
	v_mov_b32_e32 v28, v158
	v_lshlrev_b32_e32 v28, 16, v28
	v_add_f32_e32 v13, v13, v28
	v_mov_b32_e32 v28, v159
	v_cvt_pk_bf16_f32 v13, v13, s0
	global_store_short v[24:25], v13, off
	s_waitcnt vmcnt(1)
	v_lshlrev_b32_e32 v28, 16, v28
	v_add_f32_e32 v19, v19, v28
	v_mov_b32_e32 v28, v160
	v_cvt_pk_bf16_f32 v19, v19, s0
	global_store_short v[24:25], v19, off offset:32
	s_waitcnt vmcnt(1)
	v_lshlrev_b32_e32 v28, 16, v28
	v_add_f32_e32 v17, v17, v28
	v_mov_b32_e32 v28, v161
	v_cvt_pk_bf16_f32 v17, v17, s0
	global_store_short v[24:25], v17, off offset:64
	s_waitcnt vmcnt(1)
	v_lshlrev_b32_e32 v28, 16, v28
	v_add_f32_e32 v9, v9, v28
	v_cvt_pk_bf16_f32 v9, v9, s0
	global_store_short v[24:25], v9, off offset:96
	v_and_b32_e32 v25, 64, v215
	v_xor_b32_e32 v24, 1, v215
	v_add_u32_e32 v29, 64, v25
	v_cmp_lt_i32_e32 vcc, v24, v29
	v_xor_b32_e32 v25, 2, v215
	v_xor_b32_e32 v28, 4, v215
	v_cndmask_b32_e32 v24, v215, v24, vcc
	v_cmp_lt_i32_e32 vcc, v25, v29
	v_lshlrev_b32_e32 v24, 2, v24
	s_nop 0
	v_cndmask_b32_e32 v25, v215, v25, vcc
	v_cmp_lt_i32_e32 vcc, v28, v29
	v_lshlrev_b32_e32 v25, 2, v25
	s_nop 0
	v_cndmask_b32_e32 v28, v215, v28, vcc
	v_cmp_lt_i32_e32 vcc, v36, v29
	v_lshlrev_b32_e32 v28, 2, v28
	s_nop 0
	v_cndmask_b32_e32 v29, v215, v36, vcc
	ds_bpermute_b32 v36, v24, v0
	v_lshlrev_b32_e32 v29, 2, v29
	s_waitcnt lgkmcnt(0)
	v_add_f32_e32 v0, v0, v36
	ds_bpermute_b32 v36, v25, v0
	s_waitcnt lgkmcnt(0)
	v_add_f32_e32 v0, v0, v36
	ds_bpermute_b32 v36, v28, v0
	s_waitcnt lgkmcnt(0)
	v_add_f32_e32 v0, v0, v36
	ds_bpermute_b32 v36, v29, v0
	s_and_saveexec_b64 s[20:21], s[6:7]
	s_cbranch_execz .LBB0_1466
	v_lshlrev_b64 v[10:11], 7, v[10:11]
	v_lshl_add_u64 v[10:11], s[18:19], 0, v[10:11]
	s_waitcnt lgkmcnt(0)
	v_add_f32_e32 v0, v0, v36
	global_store_dword v[10:11], v0, off
